# S5 pass2 recurrence advanced two time steps per dependent hop (A squared and A*b+b formed off the chain), halving the serial FMA chain
# speedup vs baseline: 1.0044x; 1.0024x over previous
.LBB0_1787:
	s_or_b64 exec, exec, s[0:1]
	s_movk_i32 s1, 0x3200
	v_mul_lo_u32 v72, v82, s1
	v_add_u32_e32 v81, 0, v72
	s_waitcnt vmcnt(0) lgkmcnt(0)
	v_mov_b32_e32 v158, 0x5040100
	v_mov_b32_e32 v159, 0x7060302
	v_perm_b32 v24, v142, v140, v158
	v_perm_b32 v25, v142, v140, v159
	v_perm_b32 v26, v143, v141, v158
	v_perm_b32 v27, v143, v141, v159
	v_perm_b32 v20, v146, v144, v158
	v_perm_b32 v21, v146, v144, v159
	v_perm_b32 v22, v147, v145, v158
	v_perm_b32 v23, v147, v145, v159
	v_perm_b32 v16, v150, v148, v158
	v_perm_b32 v17, v150, v148, v159
	v_perm_b32 v18, v151, v149, v158
	v_perm_b32 v19, v151, v149, v159
	v_perm_b32 v12, v154, v152, v158
	v_perm_b32 v13, v154, v152, v159
	v_perm_b32 v14, v155, v153, v158
	v_perm_b32 v15, v155, v153, v159
	v_mfma_f32_16x16x32_bf16 v[84:87], v[0:3], v[32:35], 0
	v_mul_u32_u24_e32 v72, 0x210, v83
	v_lshlrev_b32_e32 v73, 2, v79
	v_lshlrev_b32_e32 v72, 2, v72
	v_mfma_f32_16x16x32_bf16 v[96:99], v[0:3], v[28:31], 0
	v_add3_u32 v73, v81, v73, v72
	v_add_u32_e32 v74, 0x400, v73
	s_nop 5
	ds_write2_b32 v73, v84, v96 offset1:16
	ds_write2_b32 v73, v85, v97 offset0:132 offset1:148
	ds_write2_b32 v74, v86, v98 offset0:8 offset1:24
	ds_write2_b32 v74, v87, v99 offset0:140 offset1:156
	v_mfma_f32_16x16x32_bf16 v[82:85], v[0:3], v[40:43], 0
	v_lshl_add_u32 v75, v78, 2, v81
	s_cmp_gt_i32 s9, 3
	s_cselect_b32 s0, 0x87, 3
	v_mfma_f32_16x16x32_bf16 v[86:89], v[0:3], v[36:39], 0
	s_nop 7
	ds_write2_b32 v73, v82, v86 offset0:32 offset1:48
	ds_write2_b32 v73, v83, v87 offset0:164 offset1:180
	ds_write2_b32 v74, v84, v88 offset0:40 offset1:56
	ds_write2_b32 v74, v85, v89 offset0:172 offset1:188
	v_mfma_f32_16x16x32_bf16 v[82:85], v[0:3], v[48:51], 0
	s_sub_i32 s0, s0, s9
	v_mul_u32_u24_e32 v94, 0x110, v79
	v_add_u32_e32 v79, 64, v75
	v_mfma_f32_16x16x32_bf16 v[86:89], v[0:3], v[44:47], 0
	s_nop 7
	ds_write2_b32 v73, v82, v86 offset0:64 offset1:80
	ds_write2_b32 v73, v83, v87 offset0:196 offset1:212
	ds_write2_b32 v74, v84, v88 offset0:72 offset1:88
	ds_write2_b32 v74, v85, v89 offset0:204 offset1:220
	v_mfma_f32_16x16x32_bf16 v[82:85], v[0:3], v[56:59], 0
	v_add_u32_e32 v86, 0x90, v75
	v_add_u32_e32 v87, 0xa0, v75
	v_add_u32_e32 v88, 0xb0, v75
	v_mfma_f32_16x16x32_bf16 v[0:3], v[0:3], v[52:55], 0
	s_nop 7
	ds_write2_b32 v73, v82, v0 offset0:96 offset1:112
	ds_write2_b32 v73, v83, v1 offset0:228 offset1:244
	ds_write2_b32 v74, v84, v2 offset0:104 offset1:120
	ds_write2_b32 v74, v85, v3 offset0:236 offset1:252
	v_lshlrev_b32_e32 v0, 1, v78
	s_waitcnt vmcnt(0) lgkmcnt(0)
	v_sub_u32_e32 v72, v75, v0
	ds_read2st64_b32 v[0:1], v75 offset1:1
	ds_read2_b32 v[140:141], v75 offset0:132 offset1:196
	v_add_u32_e32 v142, 32, v75
	ds_read2st64_b32 v[144:145], v142 offset0:4 offset1:5
	v_add_u32_e32 v143, 48, v75
	ds_read2st64_b32 v[146:147], v143 offset0:6 offset1:7
	ds_read2st64_b32 v[148:149], v79 offset0:8 offset1:9
	v_add_u32_e32 v150, 0x50, v75
	ds_read2st64_b32 v[152:153], v150 offset0:10 offset1:11
	v_add_u32_e32 v151, 0x60, v75
	ds_read2st64_b32 v[154:155], v151 offset0:12 offset1:13
	v_add_u32_e32 v156, 0x70, v75
	ds_read2st64_b32 v[158:159], v156 offset0:14 offset1:15
	v_add_u32_e32 v157, 0x80, v75
	ds_read2st64_b32 v[160:161], v157 offset0:16 offset1:17
	ds_read2st64_b32 v[162:163], v86 offset0:18 offset1:19
	ds_read2st64_b32 v[164:165], v87 offset0:20 offset1:21
	ds_read2st64_b32 v[166:167], v88 offset0:22 offset1:23
	v_add_u32_e32 v168, 0xc0, v75
	ds_read2st64_b32 v[170:171], v168 offset0:24 offset1:25
	v_add_u32_e32 v169, 0xd0, v75
	ds_read2st64_b32 v[172:173], v169 offset0:26 offset1:27
	v_add_u32_e32 v174, 0xe0, v75
	ds_read2st64_b32 v[176:177], v174 offset0:28 offset1:29
	v_add_u32_e32 v175, 0xf0, v75
	ds_read2st64_b32 v[178:179], v175 offset0:30 offset1:31
	v_mov_b32_e32 v186, v70
	v_mov_b32_e32 v187, v71
	v_mov_b32_e32 v212, 0
	v_mov_b32_e32 v213, 0
	v_pk_fma_f32 v[216:217], v[66:67], v[66:67], v[212:213] op_sel:[1,1,0] op_sel_hi:[1,0,1] neg_lo:[1,0,0]
	v_pk_fma_f32 v[208:209], v[66:67], v[66:67], v[216:217] op_sel_hi:[0,1,1]
	v_add_u32_e32 v78, 48, v75
	v_add_u32_e32 v82, 0x50, v75
	s_waitcnt lgkmcnt(0)
	v_pk_fma_f32 v[212:213], v[66:67], v[0:1], v[140:141] op_sel:[1,1,0] op_sel_hi:[1,0,1] neg_lo:[1,0,0]
	v_pk_fma_f32 v[210:211], v[66:67], v[0:1], v[212:213] op_sel_hi:[0,1,1]
	v_pk_fma_f32 v[184:185], v[66:67], v[186:187], v[0:1] op_sel:[1,1,0] op_sel_hi:[1,0,1] neg_lo:[1,0,0]
	v_pk_fma_f32 v[214:215], v[66:67], v[186:187], v[184:185] op_sel_hi:[0,1,1]
	v_pk_fma_f32 v[216:217], v[208:209], v[186:187], v[210:211] op_sel:[1,1,0] op_sel_hi:[1,0,1] neg_lo:[1,0,0]
	v_pk_fma_f32 v[188:189], v[208:209], v[186:187], v[216:217] op_sel_hi:[0,1,1]
	v_cvt_pk_bf16_f32 v190, v214, v215
	v_and_b32_e32 v191, 63, v207
	v_lshl_add_u32 v191, v191, 1, v72
	ds_write_b32 v191, v190 offset:8448
	v_add_u32_e32 v71, 32, v75
	v_add_u32_e32 v83, 0x60, v75
	v_cvt_pk_bf16_f32 v190, v188, v189
	ds_write_b32 v191, v190 offset:8720
	v_add_u32_e32 v84, 0x70, v75
	v_add_u32_e32 v85, 0x80, v75
	v_pk_fma_f32 v[212:213], v[66:67], v[144:145], v[146:147] op_sel:[1,1,0] op_sel_hi:[1,0,1] neg_lo:[1,0,0]
	v_pk_fma_f32 v[210:211], v[66:67], v[144:145], v[212:213] op_sel_hi:[0,1,1]
	v_pk_fma_f32 v[184:185], v[66:67], v[188:189], v[144:145] op_sel:[1,1,0] op_sel_hi:[1,0,1] neg_lo:[1,0,0]
	v_pk_fma_f32 v[214:215], v[66:67], v[188:189], v[184:185] op_sel_hi:[0,1,1]
	v_pk_fma_f32 v[216:217], v[208:209], v[188:189], v[210:211] op_sel:[1,1,0] op_sel_hi:[1,0,1] neg_lo:[1,0,0]
	v_pk_fma_f32 v[186:187], v[208:209], v[188:189], v[216:217] op_sel_hi:[0,1,1]
	v_cvt_pk_bf16_f32 v190, v214, v215
	ds_write_b32 v191, v190 offset:8992
	v_add_u32_e32 v89, 0xc0, v75
	v_add_u32_e32 v91, 0xd0, v75
	v_cvt_pk_bf16_f32 v190, v186, v187
	ds_write_b32 v191, v190 offset:9264
	v_add_u32_e32 v92, 0xe0, v75
	v_add_u32_e32 v93, 0xf0, v75
	v_pk_fma_f32 v[212:213], v[66:67], v[148:149], v[152:153] op_sel:[1,1,0] op_sel_hi:[1,0,1] neg_lo:[1,0,0]
	v_pk_fma_f32 v[210:211], v[66:67], v[148:149], v[212:213] op_sel_hi:[0,1,1]
	v_pk_fma_f32 v[184:185], v[66:67], v[186:187], v[148:149] op_sel:[1,1,0] op_sel_hi:[1,0,1] neg_lo:[1,0,0]
	v_pk_fma_f32 v[214:215], v[66:67], v[186:187], v[184:185] op_sel_hi:[0,1,1]
	v_pk_fma_f32 v[216:217], v[208:209], v[186:187], v[210:211] op_sel:[1,1,0] op_sel_hi:[1,0,1] neg_lo:[1,0,0]
	v_pk_fma_f32 v[188:189], v[208:209], v[186:187], v[216:217] op_sel_hi:[0,1,1]
	v_cvt_pk_bf16_f32 v190, v214, v215
	ds_write_b32 v191, v190 offset:9536
	v_mfma_f32_16x16x32_bf16 v[98:101], v[4:7], v[28:31], 0
	s_or_b32 s1, s2, 0x84
	v_cvt_pk_bf16_f32 v190, v188, v189
	ds_write_b32 v191, v190 offset:9808
	s_ashr_i32 s2, s0, 31
	v_pk_fma_f32 v[212:213], v[66:67], v[154:155], v[158:159] op_sel:[1,1,0] op_sel_hi:[1,0,1] neg_lo:[1,0,0]
	v_pk_fma_f32 v[210:211], v[66:67], v[154:155], v[212:213] op_sel_hi:[0,1,1]
	v_pk_fma_f32 v[184:185], v[66:67], v[188:189], v[154:155] op_sel:[1,1,0] op_sel_hi:[1,0,1] neg_lo:[1,0,0]
	v_pk_fma_f32 v[214:215], v[66:67], v[188:189], v[184:185] op_sel_hi:[0,1,1]
	v_pk_fma_f32 v[216:217], v[208:209], v[188:189], v[210:211] op_sel:[1,1,0] op_sel_hi:[1,0,1] neg_lo:[1,0,0]
	v_pk_fma_f32 v[186:187], v[208:209], v[188:189], v[216:217] op_sel_hi:[0,1,1]
	v_cvt_pk_bf16_f32 v190, v214, v215
	ds_write_b32 v191, v190 offset:10080
	v_cvt_pk_bf16_f32 v190, v186, v187
	ds_write_b32 v191, v190 offset:10352
	v_pk_fma_f32 v[212:213], v[66:67], v[160:161], v[162:163] op_sel:[1,1,0] op_sel_hi:[1,0,1] neg_lo:[1,0,0]
	v_pk_fma_f32 v[210:211], v[66:67], v[160:161], v[212:213] op_sel_hi:[0,1,1]
	v_pk_fma_f32 v[184:185], v[66:67], v[186:187], v[160:161] op_sel:[1,1,0] op_sel_hi:[1,0,1] neg_lo:[1,0,0]
	v_pk_fma_f32 v[214:215], v[66:67], v[186:187], v[184:185] op_sel_hi:[0,1,1]
	v_pk_fma_f32 v[216:217], v[208:209], v[186:187], v[210:211] op_sel:[1,1,0] op_sel_hi:[1,0,1] neg_lo:[1,0,0]
	v_pk_fma_f32 v[188:189], v[208:209], v[186:187], v[216:217] op_sel_hi:[0,1,1]
	v_cvt_pk_bf16_f32 v190, v214, v215
	ds_write_b32 v191, v190 offset:10624
	v_cvt_pk_bf16_f32 v190, v188, v189
	ds_write_b32 v191, v190 offset:10896
	v_pk_fma_f32 v[212:213], v[66:67], v[164:165], v[166:167] op_sel:[1,1,0] op_sel_hi:[1,0,1] neg_lo:[1,0,0]
	v_pk_fma_f32 v[210:211], v[66:67], v[164:165], v[212:213] op_sel_hi:[0,1,1]
	v_pk_fma_f32 v[184:185], v[66:67], v[188:189], v[164:165] op_sel:[1,1,0] op_sel_hi:[1,0,1] neg_lo:[1,0,0]
	v_pk_fma_f32 v[214:215], v[66:67], v[188:189], v[184:185] op_sel_hi:[0,1,1]
	v_pk_fma_f32 v[216:217], v[208:209], v[188:189], v[210:211] op_sel:[1,1,0] op_sel_hi:[1,0,1] neg_lo:[1,0,0]
	v_pk_fma_f32 v[186:187], v[208:209], v[188:189], v[216:217] op_sel_hi:[0,1,1]
	v_cvt_pk_bf16_f32 v190, v214, v215
	ds_write_b32 v191, v190 offset:11168
	v_cvt_pk_bf16_f32 v190, v186, v187
	ds_write_b32 v191, v190 offset:11440
	v_pk_fma_f32 v[212:213], v[66:67], v[170:171], v[172:173] op_sel:[1,1,0] op_sel_hi:[1,0,1] neg_lo:[1,0,0]
	v_pk_fma_f32 v[210:211], v[66:67], v[170:171], v[212:213] op_sel_hi:[0,1,1]
	v_pk_fma_f32 v[184:185], v[66:67], v[186:187], v[170:171] op_sel:[1,1,0] op_sel_hi:[1,0,1] neg_lo:[1,0,0]
	v_pk_fma_f32 v[214:215], v[66:67], v[186:187], v[184:185] op_sel_hi:[0,1,1]
	v_pk_fma_f32 v[216:217], v[208:209], v[186:187], v[210:211] op_sel:[1,1,0] op_sel_hi:[1,0,1] neg_lo:[1,0,0]
	v_pk_fma_f32 v[188:189], v[208:209], v[186:187], v[216:217] op_sel_hi:[0,1,1]
	v_cvt_pk_bf16_f32 v190, v214, v215
	ds_write_b32 v191, v190 offset:11712
	v_cvt_pk_bf16_f32 v190, v188, v189
	ds_write_b32 v191, v190 offset:11984
	v_pk_fma_f32 v[212:213], v[66:67], v[176:177], v[178:179] op_sel:[1,1,0] op_sel_hi:[1,0,1] neg_lo:[1,0,0]
	v_pk_fma_f32 v[210:211], v[66:67], v[176:177], v[212:213] op_sel_hi:[0,1,1]
	v_pk_fma_f32 v[184:185], v[66:67], v[188:189], v[176:177] op_sel:[1,1,0] op_sel_hi:[1,0,1] neg_lo:[1,0,0]
	v_pk_fma_f32 v[214:215], v[66:67], v[188:189], v[184:185] op_sel_hi:[0,1,1]
	v_pk_fma_f32 v[216:217], v[208:209], v[188:189], v[210:211] op_sel:[1,1,0] op_sel_hi:[1,0,1] neg_lo:[1,0,0]
	v_pk_fma_f32 v[186:187], v[208:209], v[188:189], v[216:217] op_sel_hi:[0,1,1]
	v_cvt_pk_bf16_f32 v190, v214, v215
	ds_write_b32 v191, v190 offset:12256
	v_mov_b32_e32 v102, v186
	v_mov_b32_e32 v103, v187
	v_cvt_pk_bf16_f32 v190, v186, v187
	ds_write_b32 v191, v190 offset:12528
	v_add3_u32 v70, v81, v128, v94
	s_waitcnt vmcnt(0) lgkmcnt(0)
	ds_read_b128 v[0:3], v70 offset:8448
	ds_read_b128 v[94:97], v70 offset:8512
	s_waitcnt lgkmcnt(1)
	v_mfma_f32_16x16x32_bf16 v[0:3], v[0:3], v[24:27], 0
	s_waitcnt lgkmcnt(0)
	v_mfma_f32_16x16x32_bf16 v[0:3], v[94:97], v[20:23], v[0:3]
	ds_read_b128 v[94:97], v70 offset:8576
	s_waitcnt lgkmcnt(0)
	v_mfma_f32_16x16x32_bf16 v[0:3], v[94:97], v[16:19], v[0:3]
	ds_read_b128 v[94:97], v70 offset:8640
	s_waitcnt lgkmcnt(0)
	v_mfma_f32_16x16x32_bf16 v[0:3], v[94:97], v[12:15], v[0:3]
	v_mfma_f32_16x16x32_bf16 v[94:97], v[4:7], v[32:35], 0
	s_nop 7
	ds_write2_b32 v73, v94, v98 offset1:16
	ds_write2_b32 v73, v95, v99 offset0:132 offset1:148
	ds_write2_b32 v74, v96, v100 offset0:8 offset1:24
	ds_write2_b32 v74, v97, v101 offset0:140 offset1:156
	v_mfma_f32_16x16x32_bf16 v[94:97], v[4:7], v[40:43], 0
	v_mfma_f32_16x16x32_bf16 v[98:101], v[4:7], v[36:39], 0
	s_nop 7
	ds_write2_b32 v73, v94, v98 offset0:32 offset1:48
	ds_write2_b32 v73, v95, v99 offset0:164 offset1:180
	ds_write2_b32 v74, v96, v100 offset0:40 offset1:56
	ds_write2_b32 v74, v97, v101 offset0:172 offset1:188
	v_mfma_f32_16x16x32_bf16 v[94:97], v[4:7], v[48:51], 0
	v_mfma_f32_16x16x32_bf16 v[98:101], v[4:7], v[44:47], 0
	s_nop 7
	ds_write2_b32 v73, v94, v98 offset0:64 offset1:80
	ds_write2_b32 v73, v95, v99 offset0:196 offset1:212
	ds_write2_b32 v74, v96, v100 offset0:72 offset1:88
	ds_write2_b32 v74, v97, v101 offset0:204 offset1:220
	v_mfma_f32_16x16x32_bf16 v[94:97], v[4:7], v[56:59], 0
	v_mfma_f32_16x16x32_bf16 v[4:7], v[4:7], v[52:55], 0
	s_nop 7
	ds_write2_b32 v73, v94, v4 offset0:96 offset1:112
	ds_write2_b32 v73, v95, v5 offset0:228 offset1:244
	ds_write2_b32 v74, v96, v6 offset0:104 offset1:120
	ds_write2_b32 v74, v97, v7 offset0:236 offset1:252
	s_waitcnt vmcnt(0) lgkmcnt(0)
	ds_read2st64_b32 v[4:5], v75 offset1:1
	ds_read2_b32 v[140:141], v75 offset0:132 offset1:196
	ds_read2st64_b32 v[142:143], v71 offset0:4 offset1:5
	ds_read2st64_b32 v[144:145], v78 offset0:6 offset1:7
	ds_read2st64_b32 v[146:147], v79 offset0:8 offset1:9
	ds_read2st64_b32 v[148:149], v82 offset0:10 offset1:11
	ds_read2st64_b32 v[150:151], v83 offset0:12 offset1:13
	ds_read2st64_b32 v[152:153], v84 offset0:14 offset1:15
	ds_read2st64_b32 v[154:155], v85 offset0:16 offset1:17
	ds_read2st64_b32 v[156:157], v86 offset0:18 offset1:19
	ds_read2st64_b32 v[158:159], v87 offset0:20 offset1:21
	ds_read2st64_b32 v[160:161], v88 offset0:22 offset1:23
	ds_read2st64_b32 v[162:163], v89 offset0:24 offset1:25
	ds_read2st64_b32 v[164:165], v91 offset0:26 offset1:27
	ds_read2st64_b32 v[166:167], v92 offset0:28 offset1:29
	ds_read2st64_b32 v[168:169], v93 offset0:30 offset1:31
	v_mov_b32_e32 v186, v102
	v_mov_b32_e32 v187, v103
	v_mov_b32_e32 v212, 0
	v_mov_b32_e32 v213, 0
	v_pk_fma_f32 v[216:217], v[66:67], v[66:67], v[212:213] op_sel:[1,1,0] op_sel_hi:[1,0,1] neg_lo:[1,0,0]
	v_pk_fma_f32 v[208:209], v[66:67], v[66:67], v[216:217] op_sel_hi:[0,1,1]
	v_mfma_f32_16x16x32_bf16 v[98:101], v[8:11], v[28:31], 0
	s_waitcnt lgkmcnt(0)
	v_pk_fma_f32 v[212:213], v[66:67], v[4:5], v[140:141] op_sel:[1,1,0] op_sel_hi:[1,0,1] neg_lo:[1,0,0]
	v_pk_fma_f32 v[210:211], v[66:67], v[4:5], v[212:213] op_sel_hi:[0,1,1]
	v_pk_fma_f32 v[184:185], v[66:67], v[186:187], v[4:5] op_sel:[1,1,0] op_sel_hi:[1,0,1] neg_lo:[1,0,0]
	v_pk_fma_f32 v[214:215], v[66:67], v[186:187], v[184:185] op_sel_hi:[0,1,1]
	v_pk_fma_f32 v[216:217], v[208:209], v[186:187], v[210:211] op_sel:[1,1,0] op_sel_hi:[1,0,1] neg_lo:[1,0,0]
	v_pk_fma_f32 v[188:189], v[208:209], v[186:187], v[216:217] op_sel_hi:[0,1,1]
	v_cvt_pk_bf16_f32 v190, v214, v215
	v_and_b32_e32 v191, 63, v207
	v_lshl_add_u32 v191, v191, 1, v72
	ds_write_b32 v191, v190 offset:8448
	v_mfma_f32_16x16x32_bf16 v[28:31], v[60:63], v[28:31], 0
	v_cvt_pk_bf16_f32 v190, v188, v189
	ds_write_b32 v191, v190 offset:8720
	v_pk_fma_f32 v[212:213], v[66:67], v[142:143], v[144:145] op_sel:[1,1,0] op_sel_hi:[1,0,1] neg_lo:[1,0,0]
	v_pk_fma_f32 v[210:211], v[66:67], v[142:143], v[212:213] op_sel_hi:[0,1,1]
	v_pk_fma_f32 v[184:185], v[66:67], v[188:189], v[142:143] op_sel:[1,1,0] op_sel_hi:[1,0,1] neg_lo:[1,0,0]
	v_pk_fma_f32 v[214:215], v[66:67], v[188:189], v[184:185] op_sel_hi:[0,1,1]
	v_pk_fma_f32 v[216:217], v[208:209], v[188:189], v[210:211] op_sel:[1,1,0] op_sel_hi:[1,0,1] neg_lo:[1,0,0]
	v_pk_fma_f32 v[186:187], v[208:209], v[188:189], v[216:217] op_sel_hi:[0,1,1]
	v_cvt_pk_bf16_f32 v190, v214, v215
	ds_write_b32 v191, v190 offset:8992
	v_cvt_pk_bf16_f32 v190, v186, v187
	ds_write_b32 v191, v190 offset:9264
	v_pk_fma_f32 v[212:213], v[66:67], v[146:147], v[148:149] op_sel:[1,1,0] op_sel_hi:[1,0,1] neg_lo:[1,0,0]
	v_pk_fma_f32 v[210:211], v[66:67], v[146:147], v[212:213] op_sel_hi:[0,1,1]
	v_pk_fma_f32 v[184:185], v[66:67], v[186:187], v[146:147] op_sel:[1,1,0] op_sel_hi:[1,0,1] neg_lo:[1,0,0]
	v_pk_fma_f32 v[214:215], v[66:67], v[186:187], v[184:185] op_sel_hi:[0,1,1]
	v_pk_fma_f32 v[216:217], v[208:209], v[186:187], v[210:211] op_sel:[1,1,0] op_sel_hi:[1,0,1] neg_lo:[1,0,0]
	v_pk_fma_f32 v[188:189], v[208:209], v[186:187], v[216:217] op_sel_hi:[0,1,1]
	v_cvt_pk_bf16_f32 v190, v214, v215
	ds_write_b32 v191, v190 offset:9536
	v_cvt_pk_bf16_f32 v190, v188, v189
	ds_write_b32 v191, v190 offset:9808
	v_pk_fma_f32 v[212:213], v[66:67], v[150:151], v[152:153] op_sel:[1,1,0] op_sel_hi:[1,0,1] neg_lo:[1,0,0]
	v_pk_fma_f32 v[210:211], v[66:67], v[150:151], v[212:213] op_sel_hi:[0,1,1]
	v_pk_fma_f32 v[184:185], v[66:67], v[188:189], v[150:151] op_sel:[1,1,0] op_sel_hi:[1,0,1] neg_lo:[1,0,0]
	v_pk_fma_f32 v[214:215], v[66:67], v[188:189], v[184:185] op_sel_hi:[0,1,1]
	v_pk_fma_f32 v[216:217], v[208:209], v[188:189], v[210:211] op_sel:[1,1,0] op_sel_hi:[1,0,1] neg_lo:[1,0,0]
	v_pk_fma_f32 v[186:187], v[208:209], v[188:189], v[216:217] op_sel_hi:[0,1,1]
	v_cvt_pk_bf16_f32 v190, v214, v215
	ds_write_b32 v191, v190 offset:10080
	v_cvt_pk_bf16_f32 v190, v186, v187
	ds_write_b32 v191, v190 offset:10352
	v_pk_fma_f32 v[212:213], v[66:67], v[154:155], v[156:157] op_sel:[1,1,0] op_sel_hi:[1,0,1] neg_lo:[1,0,0]
	v_pk_fma_f32 v[210:211], v[66:67], v[154:155], v[212:213] op_sel_hi:[0,1,1]
	v_pk_fma_f32 v[184:185], v[66:67], v[186:187], v[154:155] op_sel:[1,1,0] op_sel_hi:[1,0,1] neg_lo:[1,0,0]
	v_pk_fma_f32 v[214:215], v[66:67], v[186:187], v[184:185] op_sel_hi:[0,1,1]
	v_pk_fma_f32 v[216:217], v[208:209], v[186:187], v[210:211] op_sel:[1,1,0] op_sel_hi:[1,0,1] neg_lo:[1,0,0]
	v_pk_fma_f32 v[188:189], v[208:209], v[186:187], v[216:217] op_sel_hi:[0,1,1]
	v_cvt_pk_bf16_f32 v190, v214, v215
	ds_write_b32 v191, v190 offset:10624
	v_cvt_pk_bf16_f32 v190, v188, v189
	ds_write_b32 v191, v190 offset:10896
	v_pk_fma_f32 v[212:213], v[66:67], v[158:159], v[160:161] op_sel:[1,1,0] op_sel_hi:[1,0,1] neg_lo:[1,0,0]
	v_pk_fma_f32 v[210:211], v[66:67], v[158:159], v[212:213] op_sel_hi:[0,1,1]
	v_pk_fma_f32 v[184:185], v[66:67], v[188:189], v[158:159] op_sel:[1,1,0] op_sel_hi:[1,0,1] neg_lo:[1,0,0]
	v_pk_fma_f32 v[214:215], v[66:67], v[188:189], v[184:185] op_sel_hi:[0,1,1]
	v_pk_fma_f32 v[216:217], v[208:209], v[188:189], v[210:211] op_sel:[1,1,0] op_sel_hi:[1,0,1] neg_lo:[1,0,0]
	v_pk_fma_f32 v[186:187], v[208:209], v[188:189], v[216:217] op_sel_hi:[0,1,1]
	v_cvt_pk_bf16_f32 v190, v214, v215
	ds_write_b32 v191, v190 offset:11168
	v_cvt_pk_bf16_f32 v190, v186, v187
	ds_write_b32 v191, v190 offset:11440
	v_pk_fma_f32 v[212:213], v[66:67], v[162:163], v[164:165] op_sel:[1,1,0] op_sel_hi:[1,0,1] neg_lo:[1,0,0]
	v_pk_fma_f32 v[210:211], v[66:67], v[162:163], v[212:213] op_sel_hi:[0,1,1]
	v_pk_fma_f32 v[184:185], v[66:67], v[186:187], v[162:163] op_sel:[1,1,0] op_sel_hi:[1,0,1] neg_lo:[1,0,0]
	v_pk_fma_f32 v[214:215], v[66:67], v[186:187], v[184:185] op_sel_hi:[0,1,1]
	v_pk_fma_f32 v[216:217], v[208:209], v[186:187], v[210:211] op_sel:[1,1,0] op_sel_hi:[1,0,1] neg_lo:[1,0,0]
	v_pk_fma_f32 v[188:189], v[208:209], v[186:187], v[216:217] op_sel_hi:[0,1,1]
	v_cvt_pk_bf16_f32 v190, v214, v215
	ds_write_b32 v191, v190 offset:11712
	v_cvt_pk_bf16_f32 v190, v188, v189
	ds_write_b32 v191, v190 offset:11984
	v_pk_fma_f32 v[212:213], v[66:67], v[166:167], v[168:169] op_sel:[1,1,0] op_sel_hi:[1,0,1] neg_lo:[1,0,0]
	v_pk_fma_f32 v[210:211], v[66:67], v[166:167], v[212:213] op_sel_hi:[0,1,1]
	v_pk_fma_f32 v[184:185], v[66:67], v[188:189], v[166:167] op_sel:[1,1,0] op_sel_hi:[1,0,1] neg_lo:[1,0,0]
	v_pk_fma_f32 v[214:215], v[66:67], v[188:189], v[184:185] op_sel_hi:[0,1,1]
	v_pk_fma_f32 v[216:217], v[208:209], v[188:189], v[210:211] op_sel:[1,1,0] op_sel_hi:[1,0,1] neg_lo:[1,0,0]
	v_pk_fma_f32 v[186:187], v[208:209], v[188:189], v[216:217] op_sel_hi:[0,1,1]
	v_cvt_pk_bf16_f32 v190, v214, v215
	ds_write_b32 v191, v190 offset:12256
	v_mov_b32_e32 v102, v186
	v_mov_b32_e32 v103, v187
	v_cvt_pk_bf16_f32 v190, v186, v187
	ds_write_b32 v191, v190 offset:12528
	s_waitcnt vmcnt(0) lgkmcnt(0)
	ds_read_b128 v[4:7], v70 offset:8448
	ds_read_b128 v[94:97], v70 offset:8512
	s_waitcnt lgkmcnt(1)
	v_mfma_f32_16x16x32_bf16 v[4:7], v[4:7], v[24:27], 0
	s_waitcnt lgkmcnt(0)
	v_mfma_f32_16x16x32_bf16 v[4:7], v[94:97], v[20:23], v[4:7]
	ds_read_b128 v[94:97], v70 offset:8576
	s_waitcnt lgkmcnt(0)
	v_mfma_f32_16x16x32_bf16 v[4:7], v[94:97], v[16:19], v[4:7]
	ds_read_b128 v[94:97], v70 offset:8640
	s_waitcnt lgkmcnt(0)
	v_mfma_f32_16x16x32_bf16 v[4:7], v[94:97], v[12:15], v[4:7]
	v_mfma_f32_16x16x32_bf16 v[94:97], v[8:11], v[32:35], 0
	s_nop 7
	ds_write2_b32 v73, v94, v98 offset1:16
	ds_write2_b32 v73, v95, v99 offset0:132 offset1:148
	ds_write2_b32 v74, v96, v100 offset0:8 offset1:24
	ds_write2_b32 v74, v97, v101 offset0:140 offset1:156
	v_mfma_f32_16x16x32_bf16 v[94:97], v[8:11], v[40:43], 0
	v_mfma_f32_16x16x32_bf16 v[98:101], v[8:11], v[36:39], 0
	s_nop 7
	ds_write2_b32 v73, v94, v98 offset0:32 offset1:48
	ds_write2_b32 v73, v95, v99 offset0:164 offset1:180
	ds_write2_b32 v74, v96, v100 offset0:40 offset1:56
	ds_write2_b32 v74, v97, v101 offset0:172 offset1:188
	v_mfma_f32_16x16x32_bf16 v[94:97], v[8:11], v[48:51], 0
	v_mfma_f32_16x16x32_bf16 v[98:101], v[8:11], v[44:47], 0
	s_nop 7
	ds_write2_b32 v73, v94, v98 offset0:64 offset1:80
	ds_write2_b32 v73, v95, v99 offset0:196 offset1:212
	ds_write2_b32 v74, v96, v100 offset0:72 offset1:88
	ds_write2_b32 v74, v97, v101 offset0:204 offset1:220
	v_mfma_f32_16x16x32_bf16 v[94:97], v[8:11], v[56:59], 0
	v_mfma_f32_16x16x32_bf16 v[8:11], v[8:11], v[52:55], 0
	s_nop 7
	ds_write2_b32 v73, v94, v8 offset0:96 offset1:112
	ds_write2_b32 v73, v95, v9 offset0:228 offset1:244
	ds_write2_b32 v74, v96, v10 offset0:104 offset1:120
	ds_write2_b32 v74, v97, v11 offset0:236 offset1:252
	s_waitcnt vmcnt(0) lgkmcnt(0)
	ds_read2st64_b32 v[8:9], v75 offset1:1
	ds_read2_b32 v[140:141], v75 offset0:132 offset1:196
	ds_read2st64_b32 v[142:143], v71 offset0:4 offset1:5
	ds_read2st64_b32 v[144:145], v78 offset0:6 offset1:7
	ds_read2st64_b32 v[146:147], v79 offset0:8 offset1:9
	ds_read2st64_b32 v[148:149], v82 offset0:10 offset1:11
	ds_read2st64_b32 v[150:151], v83 offset0:12 offset1:13
	ds_read2st64_b32 v[152:153], v84 offset0:14 offset1:15
	ds_read2st64_b32 v[154:155], v85 offset0:16 offset1:17
	ds_read2st64_b32 v[156:157], v86 offset0:18 offset1:19
	ds_read2st64_b32 v[158:159], v87 offset0:20 offset1:21
	ds_read2st64_b32 v[160:161], v88 offset0:22 offset1:23
	ds_read2st64_b32 v[162:163], v89 offset0:24 offset1:25
	ds_read2st64_b32 v[164:165], v91 offset0:26 offset1:27
	ds_read2st64_b32 v[166:167], v92 offset0:28 offset1:29
	ds_read2st64_b32 v[168:169], v93 offset0:30 offset1:31
	v_mov_b32_e32 v186, v102
	v_mov_b32_e32 v187, v103
	v_mov_b32_e32 v212, 0
	v_mov_b32_e32 v213, 0
	v_pk_fma_f32 v[216:217], v[66:67], v[66:67], v[212:213] op_sel:[1,1,0] op_sel_hi:[1,0,1] neg_lo:[1,0,0]
	v_pk_fma_f32 v[208:209], v[66:67], v[66:67], v[216:217] op_sel_hi:[0,1,1]
	v_mfma_f32_16x16x32_bf16 v[32:35], v[60:63], v[32:35], 0
	s_waitcnt lgkmcnt(0)
	v_pk_fma_f32 v[212:213], v[66:67], v[8:9], v[140:141] op_sel:[1,1,0] op_sel_hi:[1,0,1] neg_lo:[1,0,0]
	v_pk_fma_f32 v[210:211], v[66:67], v[8:9], v[212:213] op_sel_hi:[0,1,1]
	v_pk_fma_f32 v[184:185], v[66:67], v[186:187], v[8:9] op_sel:[1,1,0] op_sel_hi:[1,0,1] neg_lo:[1,0,0]
	v_pk_fma_f32 v[214:215], v[66:67], v[186:187], v[184:185] op_sel_hi:[0,1,1]
	v_pk_fma_f32 v[216:217], v[208:209], v[186:187], v[210:211] op_sel:[1,1,0] op_sel_hi:[1,0,1] neg_lo:[1,0,0]
	v_pk_fma_f32 v[188:189], v[208:209], v[186:187], v[216:217] op_sel_hi:[0,1,1]
	v_cvt_pk_bf16_f32 v190, v214, v215
	v_and_b32_e32 v191, 63, v207
	v_lshl_add_u32 v191, v191, 1, v72
	ds_write_b32 v191, v190 offset:8448
	v_cvt_pk_bf16_f32 v190, v188, v189
	ds_write_b32 v191, v190 offset:8720
	v_pk_fma_f32 v[212:213], v[66:67], v[142:143], v[144:145] op_sel:[1,1,0] op_sel_hi:[1,0,1] neg_lo:[1,0,0]
	v_pk_fma_f32 v[210:211], v[66:67], v[142:143], v[212:213] op_sel_hi:[0,1,1]
	v_pk_fma_f32 v[184:185], v[66:67], v[188:189], v[142:143] op_sel:[1,1,0] op_sel_hi:[1,0,1] neg_lo:[1,0,0]
	v_pk_fma_f32 v[214:215], v[66:67], v[188:189], v[184:185] op_sel_hi:[0,1,1]
	v_pk_fma_f32 v[216:217], v[208:209], v[188:189], v[210:211] op_sel:[1,1,0] op_sel_hi:[1,0,1] neg_lo:[1,0,0]
	v_pk_fma_f32 v[186:187], v[208:209], v[188:189], v[216:217] op_sel_hi:[0,1,1]
	v_cvt_pk_bf16_f32 v190, v214, v215
	ds_write_b32 v191, v190 offset:8992
	v_cvt_pk_bf16_f32 v190, v186, v187
	ds_write_b32 v191, v190 offset:9264
	v_pk_fma_f32 v[212:213], v[66:67], v[146:147], v[148:149] op_sel:[1,1,0] op_sel_hi:[1,0,1] neg_lo:[1,0,0]
	v_pk_fma_f32 v[210:211], v[66:67], v[146:147], v[212:213] op_sel_hi:[0,1,1]
	v_pk_fma_f32 v[184:185], v[66:67], v[186:187], v[146:147] op_sel:[1,1,0] op_sel_hi:[1,0,1] neg_lo:[1,0,0]
	v_pk_fma_f32 v[214:215], v[66:67], v[186:187], v[184:185] op_sel_hi:[0,1,1]
	v_pk_fma_f32 v[216:217], v[208:209], v[186:187], v[210:211] op_sel:[1,1,0] op_sel_hi:[1,0,1] neg_lo:[1,0,0]
	v_pk_fma_f32 v[188:189], v[208:209], v[186:187], v[216:217] op_sel_hi:[0,1,1]
	v_cvt_pk_bf16_f32 v190, v214, v215
	ds_write_b32 v191, v190 offset:9536
	v_cvt_pk_bf16_f32 v190, v188, v189
	ds_write_b32 v191, v190 offset:9808
	v_pk_fma_f32 v[212:213], v[66:67], v[150:151], v[152:153] op_sel:[1,1,0] op_sel_hi:[1,0,1] neg_lo:[1,0,0]
	v_pk_fma_f32 v[210:211], v[66:67], v[150:151], v[212:213] op_sel_hi:[0,1,1]
	v_pk_fma_f32 v[184:185], v[66:67], v[188:189], v[150:151] op_sel:[1,1,0] op_sel_hi:[1,0,1] neg_lo:[1,0,0]
	v_pk_fma_f32 v[214:215], v[66:67], v[188:189], v[184:185] op_sel_hi:[0,1,1]
	v_pk_fma_f32 v[216:217], v[208:209], v[188:189], v[210:211] op_sel:[1,1,0] op_sel_hi:[1,0,1] neg_lo:[1,0,0]
	v_pk_fma_f32 v[186:187], v[208:209], v[188:189], v[216:217] op_sel_hi:[0,1,1]
	v_cvt_pk_bf16_f32 v190, v214, v215
	ds_write_b32 v191, v190 offset:10080
	v_cvt_pk_bf16_f32 v190, v186, v187
	ds_write_b32 v191, v190 offset:10352
	v_pk_fma_f32 v[212:213], v[66:67], v[154:155], v[156:157] op_sel:[1,1,0] op_sel_hi:[1,0,1] neg_lo:[1,0,0]
	v_pk_fma_f32 v[210:211], v[66:67], v[154:155], v[212:213] op_sel_hi:[0,1,1]
	v_pk_fma_f32 v[184:185], v[66:67], v[186:187], v[154:155] op_sel:[1,1,0] op_sel_hi:[1,0,1] neg_lo:[1,0,0]
	v_pk_fma_f32 v[214:215], v[66:67], v[186:187], v[184:185] op_sel_hi:[0,1,1]
	v_pk_fma_f32 v[216:217], v[208:209], v[186:187], v[210:211] op_sel:[1,1,0] op_sel_hi:[1,0,1] neg_lo:[1,0,0]
	v_pk_fma_f32 v[188:189], v[208:209], v[186:187], v[216:217] op_sel_hi:[0,1,1]
	v_cvt_pk_bf16_f32 v190, v214, v215
	ds_write_b32 v191, v190 offset:10624
	v_cvt_pk_bf16_f32 v190, v188, v189
	ds_write_b32 v191, v190 offset:10896
	v_pk_fma_f32 v[212:213], v[66:67], v[158:159], v[160:161] op_sel:[1,1,0] op_sel_hi:[1,0,1] neg_lo:[1,0,0]
	v_pk_fma_f32 v[210:211], v[66:67], v[158:159], v[212:213] op_sel_hi:[0,1,1]
	v_pk_fma_f32 v[184:185], v[66:67], v[188:189], v[158:159] op_sel:[1,1,0] op_sel_hi:[1,0,1] neg_lo:[1,0,0]
	v_pk_fma_f32 v[214:215], v[66:67], v[188:189], v[184:185] op_sel_hi:[0,1,1]
	v_pk_fma_f32 v[216:217], v[208:209], v[188:189], v[210:211] op_sel:[1,1,0] op_sel_hi:[1,0,1] neg_lo:[1,0,0]
	v_pk_fma_f32 v[186:187], v[208:209], v[188:189], v[216:217] op_sel_hi:[0,1,1]
	v_cvt_pk_bf16_f32 v190, v214, v215
	ds_write_b32 v191, v190 offset:11168
	v_cvt_pk_bf16_f32 v190, v186, v187
	ds_write_b32 v191, v190 offset:11440
	v_pk_fma_f32 v[212:213], v[66:67], v[162:163], v[164:165] op_sel:[1,1,0] op_sel_hi:[1,0,1] neg_lo:[1,0,0]
	v_pk_fma_f32 v[210:211], v[66:67], v[162:163], v[212:213] op_sel_hi:[0,1,1]
	v_pk_fma_f32 v[184:185], v[66:67], v[186:187], v[162:163] op_sel:[1,1,0] op_sel_hi:[1,0,1] neg_lo:[1,0,0]
	v_pk_fma_f32 v[214:215], v[66:67], v[186:187], v[184:185] op_sel_hi:[0,1,1]
	v_pk_fma_f32 v[216:217], v[208:209], v[186:187], v[210:211] op_sel:[1,1,0] op_sel_hi:[1,0,1] neg_lo:[1,0,0]
	v_pk_fma_f32 v[188:189], v[208:209], v[186:187], v[216:217] op_sel_hi:[0,1,1]
	v_cvt_pk_bf16_f32 v190, v214, v215
	ds_write_b32 v191, v190 offset:11712
	v_cvt_pk_bf16_f32 v190, v188, v189
	ds_write_b32 v191, v190 offset:11984
	v_pk_fma_f32 v[212:213], v[66:67], v[166:167], v[168:169] op_sel:[1,1,0] op_sel_hi:[1,0,1] neg_lo:[1,0,0]
	v_pk_fma_f32 v[210:211], v[66:67], v[166:167], v[212:213] op_sel_hi:[0,1,1]
	v_pk_fma_f32 v[184:185], v[66:67], v[188:189], v[166:167] op_sel:[1,1,0] op_sel_hi:[1,0,1] neg_lo:[1,0,0]
	v_pk_fma_f32 v[214:215], v[66:67], v[188:189], v[184:185] op_sel_hi:[0,1,1]
	v_pk_fma_f32 v[216:217], v[208:209], v[188:189], v[210:211] op_sel:[1,1,0] op_sel_hi:[1,0,1] neg_lo:[1,0,0]
	v_pk_fma_f32 v[186:187], v[208:209], v[188:189], v[216:217] op_sel_hi:[0,1,1]
	v_cvt_pk_bf16_f32 v190, v214, v215
	ds_write_b32 v191, v190 offset:12256
	v_mov_b32_e32 v98, v186
	v_mov_b32_e32 v99, v187
	v_cvt_pk_bf16_f32 v190, v186, v187
	ds_write_b32 v191, v190 offset:12528
	s_waitcnt vmcnt(0) lgkmcnt(0)
	ds_read_b128 v[8:11], v70 offset:8448
	ds_read_b128 v[94:97], v70 offset:8512
	s_waitcnt lgkmcnt(1)
	v_mfma_f32_16x16x32_bf16 v[8:11], v[8:11], v[24:27], 0
	s_waitcnt lgkmcnt(0)
	v_mfma_f32_16x16x32_bf16 v[8:11], v[94:97], v[20:23], v[8:11]
	ds_read_b128 v[94:97], v70 offset:8576
	s_waitcnt lgkmcnt(0)
	v_mfma_f32_16x16x32_bf16 v[8:11], v[94:97], v[16:19], v[8:11]
	ds_read_b128 v[94:97], v70 offset:8640
	ds_write2_b32 v73, v32, v28 offset1:16
	ds_write2_b32 v73, v33, v29 offset0:132 offset1:148
	ds_write2_b32 v74, v34, v30 offset0:8 offset1:24
	ds_write2_b32 v74, v35, v31 offset0:140 offset1:156
	v_mfma_f32_16x16x32_bf16 v[28:31], v[60:63], v[40:43], 0
	v_mov_b32_e32 v40, 0
	v_mov_b32_e32 v41, 0
	v_mov_b32_e32 v42, 0
	v_mfma_f32_16x16x32_bf16 v[32:35], v[60:63], v[36:39], 0
	s_nop 7
	ds_write2_b32 v73, v28, v32 offset0:32 offset1:48
	ds_write2_b32 v73, v29, v33 offset0:164 offset1:180
	ds_write2_b32 v74, v30, v34 offset0:40 offset1:56
	ds_write2_b32 v74, v31, v35 offset0:172 offset1:188
	v_mfma_f32_16x16x32_bf16 v[28:31], v[60:63], v[48:51], 0
	v_mov_b32_e32 v36, 0
	v_mov_b32_e32 v43, 0
	v_mfma_f32_16x16x32_bf16 v[32:35], v[60:63], v[44:47], 0
	s_nop 7
	ds_write2_b32 v73, v28, v32 offset0:64 offset1:80
	ds_write2_b32 v73, v29, v33 offset0:196 offset1:212
	ds_write2_b32 v74, v30, v34 offset0:72 offset1:88
	ds_write2_b32 v74, v31, v35 offset0:204 offset1:220
	v_mfma_f32_16x16x32_bf16 v[28:31], v[60:63], v[56:59], 0
	v_mfma_f32_16x16x32_bf16 v[32:35], v[60:63], v[52:55], 0
	s_nop 7
	ds_write2_b32 v73, v28, v32 offset0:96 offset1:112
	ds_write2_b32 v73, v29, v33 offset0:228 offset1:244
	ds_write2_b32 v74, v30, v34 offset0:104 offset1:120
	ds_write2_b32 v74, v31, v35 offset0:236 offset1:252
	s_waitcnt vmcnt(0) lgkmcnt(0)
	ds_read2st64_b32 v[28:29], v75 offset1:1
	ds_read2_b32 v[140:141], v75 offset0:132 offset1:196
	ds_read2st64_b32 v[142:143], v71 offset0:4 offset1:5
	ds_read2st64_b32 v[144:145], v78 offset0:6 offset1:7
	ds_read2st64_b32 v[146:147], v79 offset0:8 offset1:9
	ds_read2st64_b32 v[148:149], v82 offset0:10 offset1:11
	ds_read2st64_b32 v[150:151], v83 offset0:12 offset1:13
	ds_read2st64_b32 v[152:153], v84 offset0:14 offset1:15
	ds_read2st64_b32 v[154:155], v85 offset0:16 offset1:17
	ds_read2st64_b32 v[156:157], v86 offset0:18 offset1:19
	ds_read2st64_b32 v[158:159], v87 offset0:20 offset1:21
	ds_read2st64_b32 v[160:161], v88 offset0:22 offset1:23
	ds_read2st64_b32 v[162:163], v89 offset0:24 offset1:25
	ds_read2st64_b32 v[164:165], v91 offset0:26 offset1:27
	ds_read2st64_b32 v[166:167], v92 offset0:28 offset1:29
	ds_read2st64_b32 v[168:169], v93 offset0:30 offset1:31
	v_mov_b32_e32 v186, v98
	v_mov_b32_e32 v187, v99
	v_mov_b32_e32 v212, 0
	v_mov_b32_e32 v213, 0
	v_pk_fma_f32 v[216:217], v[66:67], v[66:67], v[212:213] op_sel:[1,1,0] op_sel_hi:[1,0,1] neg_lo:[1,0,0]
	v_pk_fma_f32 v[208:209], v[66:67], v[66:67], v[216:217] op_sel_hi:[0,1,1]
	s_waitcnt lgkmcnt(0)
	v_mfma_f32_16x16x32_bf16 v[8:11], v[94:97], v[12:15], v[8:11]
	v_pk_fma_f32 v[212:213], v[66:67], v[28:29], v[140:141] op_sel:[1,1,0] op_sel_hi:[1,0,1] neg_lo:[1,0,0]
	v_pk_fma_f32 v[210:211], v[66:67], v[28:29], v[212:213] op_sel_hi:[0,1,1]
	v_pk_fma_f32 v[184:185], v[66:67], v[186:187], v[28:29] op_sel:[1,1,0] op_sel_hi:[1,0,1] neg_lo:[1,0,0]
	v_pk_fma_f32 v[214:215], v[66:67], v[186:187], v[184:185] op_sel_hi:[0,1,1]
	v_pk_fma_f32 v[216:217], v[208:209], v[186:187], v[210:211] op_sel:[1,1,0] op_sel_hi:[1,0,1] neg_lo:[1,0,0]
	v_pk_fma_f32 v[188:189], v[208:209], v[186:187], v[216:217] op_sel_hi:[0,1,1]
	v_cvt_pk_bf16_f32 v190, v214, v215
	v_and_b32_e32 v191, 63, v207
	v_lshl_add_u32 v191, v191, 1, v72
	ds_write_b32 v191, v190 offset:8448
	v_cvt_pk_bf16_f32 v190, v188, v189
	ds_write_b32 v191, v190 offset:8720
	v_pk_fma_f32 v[212:213], v[66:67], v[142:143], v[144:145] op_sel:[1,1,0] op_sel_hi:[1,0,1] neg_lo:[1,0,0]
	v_pk_fma_f32 v[210:211], v[66:67], v[142:143], v[212:213] op_sel_hi:[0,1,1]
	v_pk_fma_f32 v[184:185], v[66:67], v[188:189], v[142:143] op_sel:[1,1,0] op_sel_hi:[1,0,1] neg_lo:[1,0,0]
	v_pk_fma_f32 v[214:215], v[66:67], v[188:189], v[184:185] op_sel_hi:[0,1,1]
	v_pk_fma_f32 v[216:217], v[208:209], v[188:189], v[210:211] op_sel:[1,1,0] op_sel_hi:[1,0,1] neg_lo:[1,0,0]
	v_pk_fma_f32 v[186:187], v[208:209], v[188:189], v[216:217] op_sel_hi:[0,1,1]
	v_cvt_pk_bf16_f32 v190, v214, v215
	ds_write_b32 v191, v190 offset:8992
	v_cvt_pk_bf16_f32 v190, v186, v187
	ds_write_b32 v191, v190 offset:9264
	v_pk_fma_f32 v[212:213], v[66:67], v[146:147], v[148:149] op_sel:[1,1,0] op_sel_hi:[1,0,1] neg_lo:[1,0,0]
	v_pk_fma_f32 v[210:211], v[66:67], v[146:147], v[212:213] op_sel_hi:[0,1,1]
	v_pk_fma_f32 v[184:185], v[66:67], v[186:187], v[146:147] op_sel:[1,1,0] op_sel_hi:[1,0,1] neg_lo:[1,0,0]
	v_pk_fma_f32 v[214:215], v[66:67], v[186:187], v[184:185] op_sel_hi:[0,1,1]
	v_pk_fma_f32 v[216:217], v[208:209], v[186:187], v[210:211] op_sel:[1,1,0] op_sel_hi:[1,0,1] neg_lo:[1,0,0]
	v_pk_fma_f32 v[188:189], v[208:209], v[186:187], v[216:217] op_sel_hi:[0,1,1]
	v_cvt_pk_bf16_f32 v190, v214, v215
	ds_write_b32 v191, v190 offset:9536
	v_cvt_pk_bf16_f32 v190, v188, v189
	ds_write_b32 v191, v190 offset:9808
	v_pk_fma_f32 v[212:213], v[66:67], v[150:151], v[152:153] op_sel:[1,1,0] op_sel_hi:[1,0,1] neg_lo:[1,0,0]
	v_pk_fma_f32 v[210:211], v[66:67], v[150:151], v[212:213] op_sel_hi:[0,1,1]
	v_pk_fma_f32 v[184:185], v[66:67], v[188:189], v[150:151] op_sel:[1,1,0] op_sel_hi:[1,0,1] neg_lo:[1,0,0]
	v_pk_fma_f32 v[214:215], v[66:67], v[188:189], v[184:185] op_sel_hi:[0,1,1]
	v_pk_fma_f32 v[216:217], v[208:209], v[188:189], v[210:211] op_sel:[1,1,0] op_sel_hi:[1,0,1] neg_lo:[1,0,0]
	v_pk_fma_f32 v[186:187], v[208:209], v[188:189], v[216:217] op_sel_hi:[0,1,1]
	v_cvt_pk_bf16_f32 v190, v214, v215
	ds_write_b32 v191, v190 offset:10080
	v_cvt_pk_bf16_f32 v190, v186, v187
	ds_write_b32 v191, v190 offset:10352
	v_pk_fma_f32 v[212:213], v[66:67], v[154:155], v[156:157] op_sel:[1,1,0] op_sel_hi:[1,0,1] neg_lo:[1,0,0]
	v_pk_fma_f32 v[210:211], v[66:67], v[154:155], v[212:213] op_sel_hi:[0,1,1]
	v_pk_fma_f32 v[184:185], v[66:67], v[186:187], v[154:155] op_sel:[1,1,0] op_sel_hi:[1,0,1] neg_lo:[1,0,0]
	v_pk_fma_f32 v[214:215], v[66:67], v[186:187], v[184:185] op_sel_hi:[0,1,1]
	v_pk_fma_f32 v[216:217], v[208:209], v[186:187], v[210:211] op_sel:[1,1,0] op_sel_hi:[1,0,1] neg_lo:[1,0,0]
	v_pk_fma_f32 v[188:189], v[208:209], v[186:187], v[216:217] op_sel_hi:[0,1,1]
	v_cvt_pk_bf16_f32 v190, v214, v215
	ds_write_b32 v191, v190 offset:10624
	v_cvt_pk_bf16_f32 v190, v188, v189
	ds_write_b32 v191, v190 offset:10896
	v_pk_fma_f32 v[212:213], v[66:67], v[158:159], v[160:161] op_sel:[1,1,0] op_sel_hi:[1,0,1] neg_lo:[1,0,0]
	v_pk_fma_f32 v[210:211], v[66:67], v[158:159], v[212:213] op_sel_hi:[0,1,1]
	v_pk_fma_f32 v[184:185], v[66:67], v[188:189], v[158:159] op_sel:[1,1,0] op_sel_hi:[1,0,1] neg_lo:[1,0,0]
	v_pk_fma_f32 v[214:215], v[66:67], v[188:189], v[184:185] op_sel_hi:[0,1,1]
	v_pk_fma_f32 v[216:217], v[208:209], v[188:189], v[210:211] op_sel:[1,1,0] op_sel_hi:[1,0,1] neg_lo:[1,0,0]
	v_pk_fma_f32 v[186:187], v[208:209], v[188:189], v[216:217] op_sel_hi:[0,1,1]
	v_cvt_pk_bf16_f32 v190, v214, v215
	ds_write_b32 v191, v190 offset:11168
	v_cvt_pk_bf16_f32 v190, v186, v187
	ds_write_b32 v191, v190 offset:11440
	v_pk_fma_f32 v[212:213], v[66:67], v[162:163], v[164:165] op_sel:[1,1,0] op_sel_hi:[1,0,1] neg_lo:[1,0,0]
	v_pk_fma_f32 v[210:211], v[66:67], v[162:163], v[212:213] op_sel_hi:[0,1,1]
	v_pk_fma_f32 v[184:185], v[66:67], v[186:187], v[162:163] op_sel:[1,1,0] op_sel_hi:[1,0,1] neg_lo:[1,0,0]
	v_pk_fma_f32 v[214:215], v[66:67], v[186:187], v[184:185] op_sel_hi:[0,1,1]
	v_pk_fma_f32 v[216:217], v[208:209], v[186:187], v[210:211] op_sel:[1,1,0] op_sel_hi:[1,0,1] neg_lo:[1,0,0]
	v_pk_fma_f32 v[188:189], v[208:209], v[186:187], v[216:217] op_sel_hi:[0,1,1]
	v_cvt_pk_bf16_f32 v190, v214, v215
	ds_write_b32 v191, v190 offset:11712
	v_cvt_pk_bf16_f32 v190, v188, v189
	ds_write_b32 v191, v190 offset:11984
	v_pk_fma_f32 v[212:213], v[66:67], v[166:167], v[168:169] op_sel:[1,1,0] op_sel_hi:[1,0,1] neg_lo:[1,0,0]
	v_pk_fma_f32 v[210:211], v[66:67], v[166:167], v[212:213] op_sel_hi:[0,1,1]
	v_pk_fma_f32 v[184:185], v[66:67], v[188:189], v[166:167] op_sel:[1,1,0] op_sel_hi:[1,0,1] neg_lo:[1,0,0]
	v_pk_fma_f32 v[214:215], v[66:67], v[188:189], v[184:185] op_sel_hi:[0,1,1]
	v_pk_fma_f32 v[216:217], v[208:209], v[188:189], v[210:211] op_sel:[1,1,0] op_sel_hi:[1,0,1] neg_lo:[1,0,0]
	v_pk_fma_f32 v[186:187], v[208:209], v[188:189], v[216:217] op_sel_hi:[0,1,1]
	v_cvt_pk_bf16_f32 v190, v214, v215
	ds_write_b32 v191, v190 offset:12256
	v_mov_b32_e32 v28, v186
	v_mov_b32_e32 v29, v187
	v_cvt_pk_bf16_f32 v190, v186, v187
	ds_write_b32 v191, v190 offset:12528
	s_waitcnt vmcnt(0) lgkmcnt(0)
	ds_read_b128 v[28:31], v70 offset:8448
	s_waitcnt lgkmcnt(0)
	v_mfma_f32_16x16x32_bf16 v[24:27], v[28:31], v[24:27], 0
	ds_read_b128 v[28:31], v70 offset:8512
	s_add_u32 s0, s0, s1
	s_addc_u32 s1, s2, 0
	s_waitcnt lgkmcnt(0)
	v_mfma_f32_16x16x32_bf16 v[20:23], v[28:31], v[20:23], v[24:27]
	s_nop 2
	ds_read_b128 v[24:27], v70 offset:8576
	s_lshl_b64 s[0:1], s[0:1], 14
	s_waitcnt lgkmcnt(0)
	v_mfma_f32_16x16x32_bf16 v[16:19], v[24:27], v[16:19], v[20:23]
	s_nop 2
	ds_read_b128 v[20:23], v70 offset:8640
	s_waitcnt lgkmcnt(0)
	v_mfma_f32_16x16x32_bf16 v[12:15], v[20:23], v[12:15], v[16:19]
	s_nop 2
	v_lshl_add_u64 v[16:17], v[64:65], 0, s[0:1]
	v_mov_b32_e32 v20, v207
	global_load_dwordx2 v[84:85], v[16:17], off
	v_add_u32_e32 v16, s90, v77
	v_and_b32_e32 v91, 63, v20
	v_or_b32_e32 v16, v91, v16
	v_ashrrev_i32_e32 v17, 31, v16
	v_lshl_add_u64 v[16:17], v[16:17], 3, s[60:61]
	global_load_dwordx2 v[82:83], v[16:17], off
	v_add_u32_e32 v16, s91, v76
	v_ashrrev_i32_e32 v17, 31, v16
	v_and_b32_e32 v92, 15, v20
	v_lshlrev_b64 v[16:17], 12, v[16:17]
	v_lshl_add_u64 v[18:19], s[62:63], 0, v[16:17]
	v_lshlrev_b32_e32 v21, 4, v92
	v_and_b32_e32 v128, 48, v20
	v_cmp_gt_u32_e64 s[42:43], 32, v91
	v_lshl_add_u64 v[18:19], v[18:19], 0, v[128:129]
	v_lshlrev_b32_e32 v128, 1, v21
	s_and_saveexec_b64 s[0:1], s[42:43]
	s_cbranch_execz .LBB0_1789
	v_lshl_add_u64 v[22:23], v[18:19], 0, v[128:129]
	global_load_dwordx4 v[40:43], v[22:23], off

.LBB0_1811:
	s_or_b64 exec, exec, s[0:1]
	s_waitcnt vmcnt(0) lgkmcnt(0)
	v_mov_b32_e32 v158, 0x5040100
	v_mov_b32_e32 v159, 0x7060302
	v_perm_b32 v32, v142, v140, v158
	v_perm_b32 v33, v142, v140, v159
	v_perm_b32 v34, v143, v141, v158
	v_perm_b32 v35, v143, v141, v159
	v_perm_b32 v28, v146, v144, v158
	v_perm_b32 v29, v146, v144, v159
	v_perm_b32 v30, v147, v145, v158
	v_perm_b32 v31, v147, v145, v159
	v_perm_b32 v24, v150, v148, v158
	v_perm_b32 v25, v150, v148, v159
	v_perm_b32 v26, v151, v149, v158
	v_perm_b32 v27, v151, v149, v159
	v_perm_b32 v20, v154, v152, v158
	v_perm_b32 v21, v154, v152, v159
	v_perm_b32 v22, v155, v153, v158
	v_perm_b32 v23, v155, v153, v159
	v_mfma_f32_16x16x32_bf16 v[94:97], v[16:19], v[40:43], 0
	v_mul_u32_u24_e32 v86, 0x210, v93
	v_lshlrev_b32_e32 v87, 2, v92
	v_lshlrev_b32_e32 v86, 2, v86
	v_mfma_f32_16x16x32_bf16 v[98:101], v[16:19], v[36:39], 0
	v_add3_u32 v88, v81, v87, v86
	v_add_u32_e32 v89, 0x400, v88
	v_mul_u32_u24_e32 v103, 0x110, v92
	s_nop 4
	ds_write2_b32 v88, v94, v98 offset1:16
	ds_write2_b32 v88, v95, v99 offset0:132 offset1:148
	ds_write2_b32 v89, v96, v100 offset0:8 offset1:24
	ds_write2_b32 v89, v97, v101 offset0:140 offset1:156
	v_mfma_f32_16x16x32_bf16 v[92:95], v[16:19], v[48:51], 0
	v_lshl_add_u32 v87, v91, 2, v81
	v_add3_u32 v81, v81, v128, v103
	v_pk_add_f32 v[0:1], v[0:1], 0 op_sel_hi:[1,0]
	v_mfma_f32_16x16x32_bf16 v[96:99], v[16:19], v[44:47], 0
	s_nop 7
	ds_write2_b32 v88, v92, v96 offset0:32 offset1:48
	ds_write2_b32 v88, v93, v97 offset0:164 offset1:180
	ds_write2_b32 v89, v94, v98 offset0:40 offset1:56
	ds_write2_b32 v89, v95, v99 offset0:172 offset1:188
	v_mfma_f32_16x16x32_bf16 v[92:95], v[16:19], v[56:59], 0
	v_readlane_b32 s68, v251, 41
	v_readlane_b32 s76, v251, 49
	v_readlane_b32 s77, v251, 50
	v_mfma_f32_16x16x32_bf16 v[96:99], v[16:19], v[52:55], 0
	s_nop 7
	ds_write2_b32 v88, v92, v96 offset0:64 offset1:80
	ds_write2_b32 v88, v93, v97 offset0:196 offset1:212
	ds_write2_b32 v89, v94, v98 offset0:72 offset1:88
	ds_write2_b32 v89, v95, v99 offset0:204 offset1:220
	v_mfma_f32_16x16x32_bf16 v[92:95], v[16:19], v[64:67], 0
	s_mov_b32 s10, 0x3f200000
	v_readlane_b32 s69, v251, 42
	v_readlane_b32 s70, v251, 43
	v_mfma_f32_16x16x32_bf16 v[16:19], v[16:19], v[60:63], 0
	s_nop 7
	ds_write2_b32 v88, v92, v16 offset0:96 offset1:112
	ds_write2_b32 v88, v93, v17 offset0:228 offset1:244
	ds_write2_b32 v89, v94, v18 offset0:104 offset1:120
	ds_write2_b32 v89, v95, v19 offset0:236 offset1:252
	v_lshlrev_b32_e32 v16, 1, v91
	v_add_u32_e32 v91, 0xf0, v87
	s_waitcnt vmcnt(0) lgkmcnt(0)
	v_sub_u32_e32 v86, v87, v16
	ds_read2st64_b32 v[16:17], v91 offset0:30 offset1:31
	v_add_u32_e32 v140, 0xe0, v87
	ds_read2st64_b32 v[142:143], v140 offset0:28 offset1:29
	v_add_u32_e32 v141, 0xd0, v87
	ds_read2st64_b32 v[144:145], v141 offset0:26 offset1:27
	v_add_u32_e32 v146, 0xc0, v87
	ds_read2st64_b32 v[148:149], v146 offset0:24 offset1:25
	v_add_u32_e32 v147, 0xb0, v87
	ds_read2st64_b32 v[150:151], v147 offset0:22 offset1:23
	v_add_u32_e32 v152, 0xa0, v87
	ds_read2st64_b32 v[154:155], v152 offset0:20 offset1:21
	v_add_u32_e32 v153, 0x90, v87
	ds_read2st64_b32 v[156:157], v153 offset0:18 offset1:19
	v_add_u32_e32 v158, 0x80, v87
	ds_read2st64_b32 v[160:161], v158 offset0:16 offset1:17
	v_add_u32_e32 v159, 0x70, v87
	ds_read2st64_b32 v[162:163], v159 offset0:14 offset1:15
	v_add_u32_e32 v164, 0x60, v87
	ds_read2st64_b32 v[166:167], v164 offset0:12 offset1:13
	v_add_u32_e32 v165, 0x50, v87
	ds_read2st64_b32 v[168:169], v165 offset0:10 offset1:11
	v_add_u32_e32 v170, 64, v87
	ds_read2st64_b32 v[172:173], v170 offset0:8 offset1:9
	v_add_u32_e32 v171, 48, v87
	ds_read2st64_b32 v[174:175], v171 offset0:6 offset1:7
	v_add_u32_e32 v176, 32, v87
	ds_read2st64_b32 v[178:179], v176 offset0:4 offset1:5
	ds_read2_b32 v[180:181], v87 offset0:132 offset1:196
	ds_read2st64_b32 v[182:183], v87 offset1:1
	v_mov_b32_e32 v186, v84
	v_mov_b32_e32 v187, v85
	v_mov_b32_e32 v212, 0
	v_mov_b32_e32 v213, 0
	v_pk_fma_f32 v[216:217], v[82:83], v[82:83], v[212:213] op_sel:[1,1,0] op_sel_hi:[1,0,1] neg_lo:[1,0,0]
	v_pk_fma_f32 v[208:209], v[82:83], v[82:83], v[216:217] op_sel_hi:[0,1,1]
	v_mfma_f32_16x16x32_bf16 v[108:111], v[72:75], v[36:39], 0
	v_readlane_b32 s71, v251, 44
	s_waitcnt lgkmcnt(0)
	v_pk_fma_f32 v[212:213], v[82:83], v[16:17], v[142:143] op_sel:[1,1,0] op_sel_hi:[1,0,1] neg_lo:[1,0,0]
	v_pk_fma_f32 v[210:211], v[82:83], v[16:17], v[212:213] op_sel_hi:[0,1,1]
	v_pk_fma_f32 v[184:185], v[82:83], v[186:187], v[16:17] op_sel:[1,1,0] op_sel_hi:[1,0,1] neg_lo:[1,0,0]
	v_pk_fma_f32 v[214:215], v[82:83], v[186:187], v[184:185] op_sel_hi:[0,1,1]
	v_pk_fma_f32 v[216:217], v[208:209], v[186:187], v[210:211] op_sel:[1,1,0] op_sel_hi:[1,0,1] neg_lo:[1,0,0]
	v_pk_fma_f32 v[188:189], v[208:209], v[186:187], v[216:217] op_sel_hi:[0,1,1]
	v_cvt_pk_bf16_f32 v190, v214, v215
	v_and_b32_e32 v191, 63, v207
	v_lshl_add_u32 v191, v191, 1, v86
	ds_write_b32 v191, v190 offset:12528
	v_add_u32_e32 v84, 0xe0, v87
	v_readlane_b32 s72, v251, 45
	v_readlane_b32 s73, v251, 46
	v_cvt_pk_bf16_f32 v190, v188, v189
	ds_write_b32 v191, v190 offset:12256
	v_add_u32_e32 v85, 0xd0, v87
	v_readlane_b32 s74, v251, 47
	v_readlane_b32 s75, v251, 48
	v_pk_fma_f32 v[212:213], v[82:83], v[144:145], v[148:149] op_sel:[1,1,0] op_sel_hi:[1,0,1] neg_lo:[1,0,0]
	v_pk_fma_f32 v[210:211], v[82:83], v[144:145], v[212:213] op_sel_hi:[0,1,1]
	v_pk_fma_f32 v[184:185], v[82:83], v[188:189], v[144:145] op_sel:[1,1,0] op_sel_hi:[1,0,1] neg_lo:[1,0,0]
	v_pk_fma_f32 v[214:215], v[82:83], v[188:189], v[184:185] op_sel_hi:[0,1,1]
	v_pk_fma_f32 v[216:217], v[208:209], v[188:189], v[210:211] op_sel:[1,1,0] op_sel_hi:[1,0,1] neg_lo:[1,0,0]
	v_pk_fma_f32 v[186:187], v[208:209], v[188:189], v[216:217] op_sel_hi:[0,1,1]
	v_cvt_pk_bf16_f32 v190, v214, v215
	ds_write_b32 v191, v190 offset:11984
	v_add_u32_e32 v92, 0xc0, v87
	v_readlane_b32 s78, v251, 51
	v_readlane_b32 s79, v251, 52
	v_cvt_pk_bf16_f32 v190, v186, v187
	ds_write_b32 v191, v190 offset:11712
	v_add_u32_e32 v93, 0xb0, v87
	v_readlane_b32 s80, v251, 53
	v_readlane_b32 s81, v251, 54
	v_pk_fma_f32 v[212:213], v[82:83], v[150:151], v[154:155] op_sel:[1,1,0] op_sel_hi:[1,0,1] neg_lo:[1,0,0]
	v_pk_fma_f32 v[210:211], v[82:83], v[150:151], v[212:213] op_sel_hi:[0,1,1]
	v_pk_fma_f32 v[184:185], v[82:83], v[186:187], v[150:151] op_sel:[1,1,0] op_sel_hi:[1,0,1] neg_lo:[1,0,0]
	v_pk_fma_f32 v[214:215], v[82:83], v[186:187], v[184:185] op_sel_hi:[0,1,1]
	v_pk_fma_f32 v[216:217], v[208:209], v[186:187], v[210:211] op_sel:[1,1,0] op_sel_hi:[1,0,1] neg_lo:[1,0,0]
	v_pk_fma_f32 v[188:189], v[208:209], v[186:187], v[216:217] op_sel_hi:[0,1,1]
	v_cvt_pk_bf16_f32 v190, v214, v215
	ds_write_b32 v191, v190 offset:11440
	v_add_u32_e32 v94, 0xa0, v87
	v_readlane_b32 s82, v251, 55
	v_readlane_b32 s83, v251, 56
	v_cvt_pk_bf16_f32 v190, v188, v189
	ds_write_b32 v191, v190 offset:11168
	v_add_u32_e32 v95, 0x90, v87
	v_pk_fma_f32 v[212:213], v[82:83], v[156:157], v[160:161] op_sel:[1,1,0] op_sel_hi:[1,0,1] neg_lo:[1,0,0]
	v_pk_fma_f32 v[210:211], v[82:83], v[156:157], v[212:213] op_sel_hi:[0,1,1]
	v_pk_fma_f32 v[184:185], v[82:83], v[188:189], v[156:157] op_sel:[1,1,0] op_sel_hi:[1,0,1] neg_lo:[1,0,0]
	v_pk_fma_f32 v[214:215], v[82:83], v[188:189], v[184:185] op_sel_hi:[0,1,1]
	v_pk_fma_f32 v[216:217], v[208:209], v[188:189], v[210:211] op_sel:[1,1,0] op_sel_hi:[1,0,1] neg_lo:[1,0,0]
	v_pk_fma_f32 v[186:187], v[208:209], v[188:189], v[216:217] op_sel_hi:[0,1,1]
	v_cvt_pk_bf16_f32 v190, v214, v215
	ds_write_b32 v191, v190 offset:10896
	v_add_u32_e32 v96, 0x80, v87
	v_cvt_pk_bf16_f32 v190, v186, v187
	ds_write_b32 v191, v190 offset:10624
	v_add_u32_e32 v97, 0x70, v87
	v_pk_fma_f32 v[212:213], v[82:83], v[162:163], v[166:167] op_sel:[1,1,0] op_sel_hi:[1,0,1] neg_lo:[1,0,0]
	v_pk_fma_f32 v[210:211], v[82:83], v[162:163], v[212:213] op_sel_hi:[0,1,1]
	v_pk_fma_f32 v[184:185], v[82:83], v[186:187], v[162:163] op_sel:[1,1,0] op_sel_hi:[1,0,1] neg_lo:[1,0,0]
	v_pk_fma_f32 v[214:215], v[82:83], v[186:187], v[184:185] op_sel_hi:[0,1,1]
	v_pk_fma_f32 v[216:217], v[208:209], v[186:187], v[210:211] op_sel:[1,1,0] op_sel_hi:[1,0,1] neg_lo:[1,0,0]
	v_pk_fma_f32 v[188:189], v[208:209], v[186:187], v[216:217] op_sel_hi:[0,1,1]
	v_cvt_pk_bf16_f32 v190, v214, v215
	ds_write_b32 v191, v190 offset:10352
	v_add_u32_e32 v98, 0x60, v87
	v_cvt_pk_bf16_f32 v190, v188, v189
	ds_write_b32 v191, v190 offset:10080
	v_add_u32_e32 v99, 0x50, v87
	v_pk_fma_f32 v[212:213], v[82:83], v[168:169], v[172:173] op_sel:[1,1,0] op_sel_hi:[1,0,1] neg_lo:[1,0,0]
	v_pk_fma_f32 v[210:211], v[82:83], v[168:169], v[212:213] op_sel_hi:[0,1,1]
	v_pk_fma_f32 v[184:185], v[82:83], v[188:189], v[168:169] op_sel:[1,1,0] op_sel_hi:[1,0,1] neg_lo:[1,0,0]
	v_pk_fma_f32 v[214:215], v[82:83], v[188:189], v[184:185] op_sel_hi:[0,1,1]
	v_pk_fma_f32 v[216:217], v[208:209], v[188:189], v[210:211] op_sel:[1,1,0] op_sel_hi:[1,0,1] neg_lo:[1,0,0]
	v_pk_fma_f32 v[186:187], v[208:209], v[188:189], v[216:217] op_sel_hi:[0,1,1]
	v_cvt_pk_bf16_f32 v190, v214, v215
	ds_write_b32 v191, v190 offset:9808
	v_add_u32_e32 v100, 64, v87
	v_cvt_pk_bf16_f32 v190, v186, v187
	ds_write_b32 v191, v190 offset:9536
	v_add_u32_e32 v101, 48, v87
	v_pk_fma_f32 v[212:213], v[82:83], v[174:175], v[178:179] op_sel:[1,1,0] op_sel_hi:[1,0,1] neg_lo:[1,0,0]
	v_pk_fma_f32 v[210:211], v[82:83], v[174:175], v[212:213] op_sel_hi:[0,1,1]
	v_pk_fma_f32 v[184:185], v[82:83], v[186:187], v[174:175] op_sel:[1,1,0] op_sel_hi:[1,0,1] neg_lo:[1,0,0]
	v_pk_fma_f32 v[214:215], v[82:83], v[186:187], v[184:185] op_sel_hi:[0,1,1]
	v_pk_fma_f32 v[216:217], v[208:209], v[186:187], v[210:211] op_sel:[1,1,0] op_sel_hi:[1,0,1] neg_lo:[1,0,0]
	v_pk_fma_f32 v[188:189], v[208:209], v[186:187], v[216:217] op_sel_hi:[0,1,1]
	v_cvt_pk_bf16_f32 v190, v214, v215
	ds_write_b32 v191, v190 offset:9264
	v_add_u32_e32 v102, 32, v87
	v_cvt_pk_bf16_f32 v190, v188, v189
	ds_write_b32 v191, v190 offset:8992
	v_pk_fma_f32 v[212:213], v[82:83], v[180:181], v[182:183] op_sel:[1,1,0] op_sel_hi:[1,0,1] neg_lo:[1,0,0]
	v_pk_fma_f32 v[210:211], v[82:83], v[180:181], v[212:213] op_sel_hi:[0,1,1]
	v_pk_fma_f32 v[184:185], v[82:83], v[188:189], v[180:181] op_sel:[1,1,0] op_sel_hi:[1,0,1] neg_lo:[1,0,0]
	v_pk_fma_f32 v[214:215], v[82:83], v[188:189], v[184:185] op_sel_hi:[0,1,1]
	v_pk_fma_f32 v[216:217], v[208:209], v[188:189], v[210:211] op_sel:[1,1,0] op_sel_hi:[1,0,1] neg_lo:[1,0,0]
	v_pk_fma_f32 v[186:187], v[208:209], v[188:189], v[216:217] op_sel_hi:[0,1,1]
	v_cvt_pk_bf16_f32 v190, v214, v215
	ds_write_b32 v191, v190 offset:8720
	v_mov_b32_e32 v112, v186
	v_mov_b32_e32 v113, v187
	v_cvt_pk_bf16_f32 v190, v186, v187
	ds_write_b32 v191, v190 offset:8448
	s_waitcnt vmcnt(0) lgkmcnt(0)
	ds_read_b128 v[16:19], v81 offset:8448
	ds_read_b128 v[104:107], v81 offset:8512
	s_waitcnt lgkmcnt(1)
	v_mfma_f32_16x16x32_bf16 v[16:19], v[16:19], v[32:35], 0
	s_waitcnt lgkmcnt(0)
	v_mfma_f32_16x16x32_bf16 v[16:19], v[104:107], v[28:31], v[16:19]
	ds_read_b128 v[104:107], v81 offset:8576
	s_waitcnt lgkmcnt(0)
	v_mfma_f32_16x16x32_bf16 v[16:19], v[104:107], v[24:27], v[16:19]
	ds_read_b128 v[104:107], v81 offset:8640
	s_waitcnt lgkmcnt(0)
	v_mfma_f32_16x16x32_bf16 v[16:19], v[104:107], v[20:23], v[16:19]
	v_mfma_f32_16x16x32_bf16 v[104:107], v[72:75], v[40:43], 0
	s_nop 7
	ds_write2_b32 v88, v104, v108 offset1:16
	ds_write2_b32 v88, v105, v109 offset0:132 offset1:148
	ds_write2_b32 v89, v106, v110 offset0:8 offset1:24
	ds_write2_b32 v89, v107, v111 offset0:140 offset1:156
	v_mfma_f32_16x16x32_bf16 v[104:107], v[72:75], v[48:51], 0
	v_mfma_f32_16x16x32_bf16 v[108:111], v[72:75], v[44:47], 0
	s_nop 7
	ds_write2_b32 v88, v104, v108 offset0:32 offset1:48
	ds_write2_b32 v88, v105, v109 offset0:164 offset1:180
	ds_write2_b32 v89, v106, v110 offset0:40 offset1:56
	ds_write2_b32 v89, v107, v111 offset0:172 offset1:188
	v_mfma_f32_16x16x32_bf16 v[104:107], v[72:75], v[56:59], 0
	v_mfma_f32_16x16x32_bf16 v[108:111], v[72:75], v[52:55], 0
	s_nop 7
	ds_write2_b32 v88, v104, v108 offset0:64 offset1:80
	ds_write2_b32 v88, v105, v109 offset0:196 offset1:212
	ds_write2_b32 v89, v106, v110 offset0:72 offset1:88
	ds_write2_b32 v89, v107, v111 offset0:204 offset1:220
	v_mfma_f32_16x16x32_bf16 v[104:107], v[72:75], v[64:67], 0
	v_mfma_f32_16x16x32_bf16 v[72:75], v[72:75], v[60:63], 0
	s_nop 7
	ds_write2_b32 v88, v104, v72 offset0:96 offset1:112
	ds_write2_b32 v88, v105, v73 offset0:228 offset1:244
	ds_write2_b32 v89, v106, v74 offset0:104 offset1:120
	ds_write2_b32 v89, v107, v75 offset0:236 offset1:252
	s_waitcnt vmcnt(0) lgkmcnt(0)
	ds_read2st64_b32 v[72:73], v91 offset0:30 offset1:31
	ds_read2st64_b32 v[140:141], v84 offset0:28 offset1:29
	ds_read2st64_b32 v[142:143], v85 offset0:26 offset1:27
	ds_read2st64_b32 v[144:145], v92 offset0:24 offset1:25
	ds_read2st64_b32 v[146:147], v93 offset0:22 offset1:23
	ds_read2st64_b32 v[148:149], v94 offset0:20 offset1:21
	ds_read2st64_b32 v[150:151], v95 offset0:18 offset1:19
	ds_read2st64_b32 v[152:153], v96 offset0:16 offset1:17
	ds_read2st64_b32 v[154:155], v97 offset0:14 offset1:15
	ds_read2st64_b32 v[156:157], v98 offset0:12 offset1:13
	ds_read2st64_b32 v[158:159], v99 offset0:10 offset1:11
	ds_read2st64_b32 v[160:161], v100 offset0:8 offset1:9
	ds_read2st64_b32 v[162:163], v101 offset0:6 offset1:7
	ds_read2st64_b32 v[164:165], v102 offset0:4 offset1:5
	ds_read2_b32 v[166:167], v87 offset0:132 offset1:196
	ds_read2st64_b32 v[168:169], v87 offset1:1
	v_mov_b32_e32 v186, v112
	v_mov_b32_e32 v187, v113
	v_mov_b32_e32 v212, 0
	v_mov_b32_e32 v213, 0
	v_pk_fma_f32 v[216:217], v[82:83], v[82:83], v[212:213] op_sel:[1,1,0] op_sel_hi:[1,0,1] neg_lo:[1,0,0]
	v_pk_fma_f32 v[208:209], v[82:83], v[82:83], v[216:217] op_sel_hi:[0,1,1]
	v_mfma_f32_16x16x32_bf16 v[108:111], v[76:79], v[36:39], 0
	s_waitcnt lgkmcnt(0)
	v_pk_fma_f32 v[212:213], v[82:83], v[72:73], v[140:141] op_sel:[1,1,0] op_sel_hi:[1,0,1] neg_lo:[1,0,0]
	v_pk_fma_f32 v[210:211], v[82:83], v[72:73], v[212:213] op_sel_hi:[0,1,1]
	v_pk_fma_f32 v[184:185], v[82:83], v[186:187], v[72:73] op_sel:[1,1,0] op_sel_hi:[1,0,1] neg_lo:[1,0,0]
	v_pk_fma_f32 v[214:215], v[82:83], v[186:187], v[184:185] op_sel_hi:[0,1,1]
	v_pk_fma_f32 v[216:217], v[208:209], v[186:187], v[210:211] op_sel:[1,1,0] op_sel_hi:[1,0,1] neg_lo:[1,0,0]
	v_pk_fma_f32 v[188:189], v[208:209], v[186:187], v[216:217] op_sel_hi:[0,1,1]
	v_cvt_pk_bf16_f32 v190, v214, v215
	v_and_b32_e32 v191, 63, v207
	v_lshl_add_u32 v191, v191, 1, v86
	ds_write_b32 v191, v190 offset:12528
	v_mfma_f32_16x16x32_bf16 v[36:39], v[68:71], v[36:39], 0
	v_cvt_pk_bf16_f32 v190, v188, v189
	ds_write_b32 v191, v190 offset:12256
	v_pk_fma_f32 v[212:213], v[82:83], v[142:143], v[144:145] op_sel:[1,1,0] op_sel_hi:[1,0,1] neg_lo:[1,0,0]
	v_pk_fma_f32 v[210:211], v[82:83], v[142:143], v[212:213] op_sel_hi:[0,1,1]
	v_pk_fma_f32 v[184:185], v[82:83], v[188:189], v[142:143] op_sel:[1,1,0] op_sel_hi:[1,0,1] neg_lo:[1,0,0]
	v_pk_fma_f32 v[214:215], v[82:83], v[188:189], v[184:185] op_sel_hi:[0,1,1]
	v_pk_fma_f32 v[216:217], v[208:209], v[188:189], v[210:211] op_sel:[1,1,0] op_sel_hi:[1,0,1] neg_lo:[1,0,0]
	v_pk_fma_f32 v[186:187], v[208:209], v[188:189], v[216:217] op_sel_hi:[0,1,1]
	v_cvt_pk_bf16_f32 v190, v214, v215
	ds_write_b32 v191, v190 offset:11984
	v_cvt_pk_bf16_f32 v190, v186, v187
	ds_write_b32 v191, v190 offset:11712
	v_pk_fma_f32 v[212:213], v[82:83], v[146:147], v[148:149] op_sel:[1,1,0] op_sel_hi:[1,0,1] neg_lo:[1,0,0]
	v_pk_fma_f32 v[210:211], v[82:83], v[146:147], v[212:213] op_sel_hi:[0,1,1]
	v_pk_fma_f32 v[184:185], v[82:83], v[186:187], v[146:147] op_sel:[1,1,0] op_sel_hi:[1,0,1] neg_lo:[1,0,0]
	v_pk_fma_f32 v[214:215], v[82:83], v[186:187], v[184:185] op_sel_hi:[0,1,1]
	v_pk_fma_f32 v[216:217], v[208:209], v[186:187], v[210:211] op_sel:[1,1,0] op_sel_hi:[1,0,1] neg_lo:[1,0,0]
	v_pk_fma_f32 v[188:189], v[208:209], v[186:187], v[216:217] op_sel_hi:[0,1,1]
	v_cvt_pk_bf16_f32 v190, v214, v215
	ds_write_b32 v191, v190 offset:11440
	v_cvt_pk_bf16_f32 v190, v188, v189
	ds_write_b32 v191, v190 offset:11168
	v_pk_fma_f32 v[212:213], v[82:83], v[150:151], v[152:153] op_sel:[1,1,0] op_sel_hi:[1,0,1] neg_lo:[1,0,0]
	v_pk_fma_f32 v[210:211], v[82:83], v[150:151], v[212:213] op_sel_hi:[0,1,1]
	v_pk_fma_f32 v[184:185], v[82:83], v[188:189], v[150:151] op_sel:[1,1,0] op_sel_hi:[1,0,1] neg_lo:[1,0,0]
	v_pk_fma_f32 v[214:215], v[82:83], v[188:189], v[184:185] op_sel_hi:[0,1,1]
	v_pk_fma_f32 v[216:217], v[208:209], v[188:189], v[210:211] op_sel:[1,1,0] op_sel_hi:[1,0,1] neg_lo:[1,0,0]
	v_pk_fma_f32 v[186:187], v[208:209], v[188:189], v[216:217] op_sel_hi:[0,1,1]
	v_cvt_pk_bf16_f32 v190, v214, v215
	ds_write_b32 v191, v190 offset:10896
	v_cvt_pk_bf16_f32 v190, v186, v187
	ds_write_b32 v191, v190 offset:10624
	v_pk_fma_f32 v[212:213], v[82:83], v[154:155], v[156:157] op_sel:[1,1,0] op_sel_hi:[1,0,1] neg_lo:[1,0,0]
	v_pk_fma_f32 v[210:211], v[82:83], v[154:155], v[212:213] op_sel_hi:[0,1,1]
	v_pk_fma_f32 v[184:185], v[82:83], v[186:187], v[154:155] op_sel:[1,1,0] op_sel_hi:[1,0,1] neg_lo:[1,0,0]
	v_pk_fma_f32 v[214:215], v[82:83], v[186:187], v[184:185] op_sel_hi:[0,1,1]
	v_pk_fma_f32 v[216:217], v[208:209], v[186:187], v[210:211] op_sel:[1,1,0] op_sel_hi:[1,0,1] neg_lo:[1,0,0]
	v_pk_fma_f32 v[188:189], v[208:209], v[186:187], v[216:217] op_sel_hi:[0,1,1]
	v_cvt_pk_bf16_f32 v190, v214, v215
	ds_write_b32 v191, v190 offset:10352
	v_cvt_pk_bf16_f32 v190, v188, v189
	ds_write_b32 v191, v190 offset:10080
	v_pk_fma_f32 v[212:213], v[82:83], v[158:159], v[160:161] op_sel:[1,1,0] op_sel_hi:[1,0,1] neg_lo:[1,0,0]
	v_pk_fma_f32 v[210:211], v[82:83], v[158:159], v[212:213] op_sel_hi:[0,1,1]
	v_pk_fma_f32 v[184:185], v[82:83], v[188:189], v[158:159] op_sel:[1,1,0] op_sel_hi:[1,0,1] neg_lo:[1,0,0]
	v_pk_fma_f32 v[214:215], v[82:83], v[188:189], v[184:185] op_sel_hi:[0,1,1]
	v_pk_fma_f32 v[216:217], v[208:209], v[188:189], v[210:211] op_sel:[1,1,0] op_sel_hi:[1,0,1] neg_lo:[1,0,0]
	v_pk_fma_f32 v[186:187], v[208:209], v[188:189], v[216:217] op_sel_hi:[0,1,1]
	v_cvt_pk_bf16_f32 v190, v214, v215
	ds_write_b32 v191, v190 offset:9808
	v_cvt_pk_bf16_f32 v190, v186, v187
	ds_write_b32 v191, v190 offset:9536
	v_pk_fma_f32 v[212:213], v[82:83], v[162:163], v[164:165] op_sel:[1,1,0] op_sel_hi:[1,0,1] neg_lo:[1,0,0]
	v_pk_fma_f32 v[210:211], v[82:83], v[162:163], v[212:213] op_sel_hi:[0,1,1]
	v_pk_fma_f32 v[184:185], v[82:83], v[186:187], v[162:163] op_sel:[1,1,0] op_sel_hi:[1,0,1] neg_lo:[1,0,0]
	v_pk_fma_f32 v[214:215], v[82:83], v[186:187], v[184:185] op_sel_hi:[0,1,1]
	v_pk_fma_f32 v[216:217], v[208:209], v[186:187], v[210:211] op_sel:[1,1,0] op_sel_hi:[1,0,1] neg_lo:[1,0,0]
	v_pk_fma_f32 v[188:189], v[208:209], v[186:187], v[216:217] op_sel_hi:[0,1,1]
	v_cvt_pk_bf16_f32 v190, v214, v215
	ds_write_b32 v191, v190 offset:9264
	v_cvt_pk_bf16_f32 v190, v188, v189
	ds_write_b32 v191, v190 offset:8992
	v_pk_fma_f32 v[212:213], v[82:83], v[166:167], v[168:169] op_sel:[1,1,0] op_sel_hi:[1,0,1] neg_lo:[1,0,0]
	v_pk_fma_f32 v[210:211], v[82:83], v[166:167], v[212:213] op_sel_hi:[0,1,1]
	v_pk_fma_f32 v[184:185], v[82:83], v[188:189], v[166:167] op_sel:[1,1,0] op_sel_hi:[1,0,1] neg_lo:[1,0,0]
	v_pk_fma_f32 v[214:215], v[82:83], v[188:189], v[184:185] op_sel_hi:[0,1,1]
	v_pk_fma_f32 v[216:217], v[208:209], v[188:189], v[210:211] op_sel:[1,1,0] op_sel_hi:[1,0,1] neg_lo:[1,0,0]
	v_pk_fma_f32 v[186:187], v[208:209], v[188:189], v[216:217] op_sel_hi:[0,1,1]
	v_cvt_pk_bf16_f32 v190, v214, v215
	ds_write_b32 v191, v190 offset:8720
	v_mov_b32_e32 v103, v186
	v_mov_b32_e32 v112, v187
	v_cvt_pk_bf16_f32 v190, v186, v187
	ds_write_b32 v191, v190 offset:8448
	s_waitcnt vmcnt(0) lgkmcnt(0)
	ds_read_b128 v[72:75], v81 offset:8448
	ds_read_b128 v[104:107], v81 offset:8512
	s_waitcnt lgkmcnt(1)
	v_mfma_f32_16x16x32_bf16 v[72:75], v[72:75], v[32:35], 0
	s_waitcnt lgkmcnt(0)
	v_mfma_f32_16x16x32_bf16 v[72:75], v[104:107], v[28:31], v[72:75]
	ds_read_b128 v[104:107], v81 offset:8576
	s_waitcnt lgkmcnt(0)
	v_mfma_f32_16x16x32_bf16 v[72:75], v[104:107], v[24:27], v[72:75]
	ds_read_b128 v[104:107], v81 offset:8640
	s_waitcnt lgkmcnt(0)
	v_mfma_f32_16x16x32_bf16 v[72:75], v[104:107], v[20:23], v[72:75]
	v_mfma_f32_16x16x32_bf16 v[104:107], v[76:79], v[40:43], 0
	s_nop 7
	ds_write2_b32 v88, v104, v108 offset1:16
	ds_write2_b32 v88, v105, v109 offset0:132 offset1:148
	ds_write2_b32 v89, v106, v110 offset0:8 offset1:24
	ds_write2_b32 v89, v107, v111 offset0:140 offset1:156
	v_mfma_f32_16x16x32_bf16 v[104:107], v[76:79], v[48:51], 0
	v_mfma_f32_16x16x32_bf16 v[108:111], v[76:79], v[44:47], 0
	s_nop 7
	ds_write2_b32 v88, v104, v108 offset0:32 offset1:48
	ds_write2_b32 v88, v105, v109 offset0:164 offset1:180
	ds_write2_b32 v89, v106, v110 offset0:40 offset1:56
	ds_write2_b32 v89, v107, v111 offset0:172 offset1:188
	v_mfma_f32_16x16x32_bf16 v[104:107], v[76:79], v[56:59], 0
	v_mfma_f32_16x16x32_bf16 v[108:111], v[76:79], v[52:55], 0
	s_nop 7
	ds_write2_b32 v88, v104, v108 offset0:64 offset1:80
	ds_write2_b32 v88, v105, v109 offset0:196 offset1:212
	ds_write2_b32 v89, v106, v110 offset0:72 offset1:88
	ds_write2_b32 v89, v107, v111 offset0:204 offset1:220
	v_mfma_f32_16x16x32_bf16 v[104:107], v[76:79], v[64:67], 0
	v_mfma_f32_16x16x32_bf16 v[76:79], v[76:79], v[60:63], 0
	s_nop 7
	ds_write2_b32 v88, v104, v76 offset0:96 offset1:112
	ds_write2_b32 v88, v105, v77 offset0:228 offset1:244
	ds_write2_b32 v89, v106, v78 offset0:104 offset1:120
	ds_write2_b32 v89, v107, v79 offset0:236 offset1:252
	s_waitcnt vmcnt(0) lgkmcnt(0)
	ds_read2st64_b32 v[76:77], v91 offset0:30 offset1:31
	ds_read2st64_b32 v[140:141], v84 offset0:28 offset1:29
	ds_read2st64_b32 v[142:143], v85 offset0:26 offset1:27
	ds_read2st64_b32 v[144:145], v92 offset0:24 offset1:25
	ds_read2st64_b32 v[146:147], v93 offset0:22 offset1:23
	ds_read2st64_b32 v[148:149], v94 offset0:20 offset1:21
	ds_read2st64_b32 v[150:151], v95 offset0:18 offset1:19
	ds_read2st64_b32 v[152:153], v96 offset0:16 offset1:17
	ds_read2st64_b32 v[154:155], v97 offset0:14 offset1:15
	ds_read2st64_b32 v[156:157], v98 offset0:12 offset1:13
	ds_read2st64_b32 v[158:159], v99 offset0:10 offset1:11
	ds_read2st64_b32 v[160:161], v100 offset0:8 offset1:9
	ds_read2st64_b32 v[162:163], v101 offset0:6 offset1:7
	ds_read2st64_b32 v[164:165], v102 offset0:4 offset1:5
	ds_read2_b32 v[166:167], v87 offset0:132 offset1:196
	ds_read2st64_b32 v[168:169], v87 offset1:1
	v_mov_b32_e32 v186, v103
	v_mov_b32_e32 v187, v112
	v_mov_b32_e32 v212, 0
	v_mov_b32_e32 v213, 0
	v_pk_fma_f32 v[216:217], v[82:83], v[82:83], v[212:213] op_sel:[1,1,0] op_sel_hi:[1,0,1] neg_lo:[1,0,0]
	v_pk_fma_f32 v[208:209], v[82:83], v[82:83], v[216:217] op_sel_hi:[0,1,1]
	v_mfma_f32_16x16x32_bf16 v[40:43], v[68:71], v[40:43], 0
	s_waitcnt lgkmcnt(0)
	v_pk_fma_f32 v[212:213], v[82:83], v[76:77], v[140:141] op_sel:[1,1,0] op_sel_hi:[1,0,1] neg_lo:[1,0,0]
	v_pk_fma_f32 v[210:211], v[82:83], v[76:77], v[212:213] op_sel_hi:[0,1,1]
	v_pk_fma_f32 v[184:185], v[82:83], v[186:187], v[76:77] op_sel:[1,1,0] op_sel_hi:[1,0,1] neg_lo:[1,0,0]
	v_pk_fma_f32 v[214:215], v[82:83], v[186:187], v[184:185] op_sel_hi:[0,1,1]
	v_pk_fma_f32 v[216:217], v[208:209], v[186:187], v[210:211] op_sel:[1,1,0] op_sel_hi:[1,0,1] neg_lo:[1,0,0]
	v_pk_fma_f32 v[188:189], v[208:209], v[186:187], v[216:217] op_sel_hi:[0,1,1]
	v_cvt_pk_bf16_f32 v190, v214, v215
	v_and_b32_e32 v191, 63, v207
	v_lshl_add_u32 v191, v191, 1, v86
	ds_write_b32 v191, v190 offset:12528
	v_cvt_pk_bf16_f32 v190, v188, v189
	ds_write_b32 v191, v190 offset:12256
	v_pk_fma_f32 v[212:213], v[82:83], v[142:143], v[144:145] op_sel:[1,1,0] op_sel_hi:[1,0,1] neg_lo:[1,0,0]
	v_pk_fma_f32 v[210:211], v[82:83], v[142:143], v[212:213] op_sel_hi:[0,1,1]
	v_pk_fma_f32 v[184:185], v[82:83], v[188:189], v[142:143] op_sel:[1,1,0] op_sel_hi:[1,0,1] neg_lo:[1,0,0]
	v_pk_fma_f32 v[214:215], v[82:83], v[188:189], v[184:185] op_sel_hi:[0,1,1]
	v_pk_fma_f32 v[216:217], v[208:209], v[188:189], v[210:211] op_sel:[1,1,0] op_sel_hi:[1,0,1] neg_lo:[1,0,0]
	v_pk_fma_f32 v[186:187], v[208:209], v[188:189], v[216:217] op_sel_hi:[0,1,1]
	v_cvt_pk_bf16_f32 v190, v214, v215
	ds_write_b32 v191, v190 offset:11984
	v_cvt_pk_bf16_f32 v190, v186, v187
	ds_write_b32 v191, v190 offset:11712
	v_pk_fma_f32 v[212:213], v[82:83], v[146:147], v[148:149] op_sel:[1,1,0] op_sel_hi:[1,0,1] neg_lo:[1,0,0]
	v_pk_fma_f32 v[210:211], v[82:83], v[146:147], v[212:213] op_sel_hi:[0,1,1]
	v_pk_fma_f32 v[184:185], v[82:83], v[186:187], v[146:147] op_sel:[1,1,0] op_sel_hi:[1,0,1] neg_lo:[1,0,0]
	v_pk_fma_f32 v[214:215], v[82:83], v[186:187], v[184:185] op_sel_hi:[0,1,1]
	v_pk_fma_f32 v[216:217], v[208:209], v[186:187], v[210:211] op_sel:[1,1,0] op_sel_hi:[1,0,1] neg_lo:[1,0,0]
	v_pk_fma_f32 v[188:189], v[208:209], v[186:187], v[216:217] op_sel_hi:[0,1,1]
	v_cvt_pk_bf16_f32 v190, v214, v215
	ds_write_b32 v191, v190 offset:11440
	v_cvt_pk_bf16_f32 v190, v188, v189
	ds_write_b32 v191, v190 offset:11168
	v_pk_fma_f32 v[212:213], v[82:83], v[150:151], v[152:153] op_sel:[1,1,0] op_sel_hi:[1,0,1] neg_lo:[1,0,0]
	v_pk_fma_f32 v[210:211], v[82:83], v[150:151], v[212:213] op_sel_hi:[0,1,1]
	v_pk_fma_f32 v[184:185], v[82:83], v[188:189], v[150:151] op_sel:[1,1,0] op_sel_hi:[1,0,1] neg_lo:[1,0,0]
	v_pk_fma_f32 v[214:215], v[82:83], v[188:189], v[184:185] op_sel_hi:[0,1,1]
	v_pk_fma_f32 v[216:217], v[208:209], v[188:189], v[210:211] op_sel:[1,1,0] op_sel_hi:[1,0,1] neg_lo:[1,0,0]
	v_pk_fma_f32 v[186:187], v[208:209], v[188:189], v[216:217] op_sel_hi:[0,1,1]
	v_cvt_pk_bf16_f32 v190, v214, v215
	ds_write_b32 v191, v190 offset:10896
	v_cvt_pk_bf16_f32 v190, v186, v187
	ds_write_b32 v191, v190 offset:10624
	v_pk_fma_f32 v[212:213], v[82:83], v[154:155], v[156:157] op_sel:[1,1,0] op_sel_hi:[1,0,1] neg_lo:[1,0,0]
	v_pk_fma_f32 v[210:211], v[82:83], v[154:155], v[212:213] op_sel_hi:[0,1,1]
	v_pk_fma_f32 v[184:185], v[82:83], v[186:187], v[154:155] op_sel:[1,1,0] op_sel_hi:[1,0,1] neg_lo:[1,0,0]
	v_pk_fma_f32 v[214:215], v[82:83], v[186:187], v[184:185] op_sel_hi:[0,1,1]
	v_pk_fma_f32 v[216:217], v[208:209], v[186:187], v[210:211] op_sel:[1,1,0] op_sel_hi:[1,0,1] neg_lo:[1,0,0]
	v_pk_fma_f32 v[188:189], v[208:209], v[186:187], v[216:217] op_sel_hi:[0,1,1]
	v_cvt_pk_bf16_f32 v190, v214, v215
	ds_write_b32 v191, v190 offset:10352
	v_cvt_pk_bf16_f32 v190, v188, v189
	ds_write_b32 v191, v190 offset:10080
	v_pk_fma_f32 v[212:213], v[82:83], v[158:159], v[160:161] op_sel:[1,1,0] op_sel_hi:[1,0,1] neg_lo:[1,0,0]
	v_pk_fma_f32 v[210:211], v[82:83], v[158:159], v[212:213] op_sel_hi:[0,1,1]
	v_pk_fma_f32 v[184:185], v[82:83], v[188:189], v[158:159] op_sel:[1,1,0] op_sel_hi:[1,0,1] neg_lo:[1,0,0]
	v_pk_fma_f32 v[214:215], v[82:83], v[188:189], v[184:185] op_sel_hi:[0,1,1]
	v_pk_fma_f32 v[216:217], v[208:209], v[188:189], v[210:211] op_sel:[1,1,0] op_sel_hi:[1,0,1] neg_lo:[1,0,0]
	v_pk_fma_f32 v[186:187], v[208:209], v[188:189], v[216:217] op_sel_hi:[0,1,1]
	v_cvt_pk_bf16_f32 v190, v214, v215
	ds_write_b32 v191, v190 offset:9808
	v_cvt_pk_bf16_f32 v190, v186, v187
	ds_write_b32 v191, v190 offset:9536
	v_pk_fma_f32 v[212:213], v[82:83], v[162:163], v[164:165] op_sel:[1,1,0] op_sel_hi:[1,0,1] neg_lo:[1,0,0]
	v_pk_fma_f32 v[210:211], v[82:83], v[162:163], v[212:213] op_sel_hi:[0,1,1]
	v_pk_fma_f32 v[184:185], v[82:83], v[186:187], v[162:163] op_sel:[1,1,0] op_sel_hi:[1,0,1] neg_lo:[1,0,0]
	v_pk_fma_f32 v[214:215], v[82:83], v[186:187], v[184:185] op_sel_hi:[0,1,1]
	v_pk_fma_f32 v[216:217], v[208:209], v[186:187], v[210:211] op_sel:[1,1,0] op_sel_hi:[1,0,1] neg_lo:[1,0,0]
	v_pk_fma_f32 v[188:189], v[208:209], v[186:187], v[216:217] op_sel_hi:[0,1,1]
	v_cvt_pk_bf16_f32 v190, v214, v215
	ds_write_b32 v191, v190 offset:9264
	v_cvt_pk_bf16_f32 v190, v188, v189
	ds_write_b32 v191, v190 offset:8992
	v_pk_fma_f32 v[212:213], v[82:83], v[166:167], v[168:169] op_sel:[1,1,0] op_sel_hi:[1,0,1] neg_lo:[1,0,0]
	v_pk_fma_f32 v[210:211], v[82:83], v[166:167], v[212:213] op_sel_hi:[0,1,1]
	v_pk_fma_f32 v[184:185], v[82:83], v[188:189], v[166:167] op_sel:[1,1,0] op_sel_hi:[1,0,1] neg_lo:[1,0,0]
	v_pk_fma_f32 v[214:215], v[82:83], v[188:189], v[184:185] op_sel_hi:[0,1,1]
	v_pk_fma_f32 v[216:217], v[208:209], v[188:189], v[210:211] op_sel:[1,1,0] op_sel_hi:[1,0,1] neg_lo:[1,0,0]
	v_pk_fma_f32 v[186:187], v[208:209], v[188:189], v[216:217] op_sel_hi:[0,1,1]
	v_cvt_pk_bf16_f32 v190, v214, v215
	ds_write_b32 v191, v190 offset:8720
	v_mov_b32_e32 v103, v186
	v_mov_b32_e32 v108, v187
	v_cvt_pk_bf16_f32 v190, v186, v187
	ds_write_b32 v191, v190 offset:8448
	s_waitcnt vmcnt(0) lgkmcnt(0)
	ds_read_b128 v[76:79], v81 offset:8448
	ds_read_b128 v[104:107], v81 offset:8512
	s_waitcnt lgkmcnt(1)
	v_mfma_f32_16x16x32_bf16 v[76:79], v[76:79], v[32:35], 0
	s_waitcnt lgkmcnt(0)
	v_mfma_f32_16x16x32_bf16 v[76:79], v[104:107], v[28:31], v[76:79]
	ds_read_b128 v[104:107], v81 offset:8576
	s_waitcnt lgkmcnt(0)
	v_mfma_f32_16x16x32_bf16 v[76:79], v[104:107], v[24:27], v[76:79]
	ds_read_b128 v[104:107], v81 offset:8640
	ds_write2_b32 v88, v40, v36 offset1:16
	ds_write2_b32 v88, v41, v37 offset0:132 offset1:148
	ds_write2_b32 v89, v42, v38 offset0:8 offset1:24
	ds_write2_b32 v89, v43, v39 offset0:140 offset1:156
	v_mfma_f32_16x16x32_bf16 v[36:39], v[68:71], v[48:51], 0
	v_mfma_f32_16x16x32_bf16 v[40:43], v[68:71], v[44:47], 0
	s_nop 7
	ds_write2_b32 v88, v36, v40 offset0:32 offset1:48
	ds_write2_b32 v88, v37, v41 offset0:164 offset1:180
	ds_write2_b32 v89, v38, v42 offset0:40 offset1:56
	ds_write2_b32 v89, v39, v43 offset0:172 offset1:188
	v_mfma_f32_16x16x32_bf16 v[36:39], v[68:71], v[56:59], 0
	v_mfma_f32_16x16x32_bf16 v[40:43], v[68:71], v[52:55], 0
	s_nop 7
	ds_write2_b32 v88, v36, v40 offset0:64 offset1:80
	ds_write2_b32 v88, v37, v41 offset0:196 offset1:212
	ds_write2_b32 v89, v38, v42 offset0:72 offset1:88
	ds_write2_b32 v89, v39, v43 offset0:204 offset1:220
	v_mfma_f32_16x16x32_bf16 v[36:39], v[68:71], v[64:67], 0
	v_mfma_f32_16x16x32_bf16 v[40:43], v[68:71], v[60:63], 0
	s_nop 7
	ds_write2_b32 v88, v36, v40 offset0:96 offset1:112
	ds_write2_b32 v88, v37, v41 offset0:228 offset1:244
	ds_write2_b32 v89, v38, v42 offset0:104 offset1:120
	ds_write2_b32 v89, v39, v43 offset0:236 offset1:252
	s_waitcnt vmcnt(0) lgkmcnt(0)
	ds_read2st64_b32 v[36:37], v91 offset0:30 offset1:31
	ds_read2st64_b32 v[140:141], v84 offset0:28 offset1:29
	ds_read2st64_b32 v[142:143], v85 offset0:26 offset1:27
	ds_read2st64_b32 v[144:145], v92 offset0:24 offset1:25
	ds_read2st64_b32 v[146:147], v93 offset0:22 offset1:23
	ds_read2st64_b32 v[148:149], v94 offset0:20 offset1:21
	ds_read2st64_b32 v[150:151], v95 offset0:18 offset1:19
	ds_read2st64_b32 v[152:153], v96 offset0:16 offset1:17
	ds_read2st64_b32 v[154:155], v97 offset0:14 offset1:15
	ds_read2st64_b32 v[156:157], v98 offset0:12 offset1:13
	ds_read2st64_b32 v[158:159], v99 offset0:10 offset1:11
	ds_read2st64_b32 v[160:161], v100 offset0:8 offset1:9
	ds_read2st64_b32 v[162:163], v101 offset0:6 offset1:7
	ds_read2st64_b32 v[164:165], v102 offset0:4 offset1:5
	ds_read2_b32 v[166:167], v87 offset0:132 offset1:196
	ds_read2st64_b32 v[168:169], v87 offset1:1
	v_mov_b32_e32 v186, v103
	v_mov_b32_e32 v187, v108
	v_mov_b32_e32 v212, 0
	v_mov_b32_e32 v213, 0
	v_pk_fma_f32 v[216:217], v[82:83], v[82:83], v[212:213] op_sel:[1,1,0] op_sel_hi:[1,0,1] neg_lo:[1,0,0]
	v_pk_fma_f32 v[208:209], v[82:83], v[82:83], v[216:217] op_sel_hi:[0,1,1]
	s_waitcnt lgkmcnt(0)
	v_mfma_f32_16x16x32_bf16 v[76:79], v[104:107], v[20:23], v[76:79]
	v_pk_fma_f32 v[212:213], v[82:83], v[36:37], v[140:141] op_sel:[1,1,0] op_sel_hi:[1,0,1] neg_lo:[1,0,0]
	v_pk_fma_f32 v[210:211], v[82:83], v[36:37], v[212:213] op_sel_hi:[0,1,1]
	v_pk_fma_f32 v[184:185], v[82:83], v[186:187], v[36:37] op_sel:[1,1,0] op_sel_hi:[1,0,1] neg_lo:[1,0,0]
	v_pk_fma_f32 v[214:215], v[82:83], v[186:187], v[184:185] op_sel_hi:[0,1,1]
	v_pk_fma_f32 v[216:217], v[208:209], v[186:187], v[210:211] op_sel:[1,1,0] op_sel_hi:[1,0,1] neg_lo:[1,0,0]
	v_pk_fma_f32 v[188:189], v[208:209], v[186:187], v[216:217] op_sel_hi:[0,1,1]
	v_cvt_pk_bf16_f32 v190, v214, v215
	v_and_b32_e32 v191, 63, v207
	v_lshl_add_u32 v191, v191, 1, v86
	ds_write_b32 v191, v190 offset:12528
	v_cvt_pk_bf16_f32 v190, v188, v189
	ds_write_b32 v191, v190 offset:12256
	v_pk_fma_f32 v[212:213], v[82:83], v[142:143], v[144:145] op_sel:[1,1,0] op_sel_hi:[1,0,1] neg_lo:[1,0,0]
	v_pk_fma_f32 v[210:211], v[82:83], v[142:143], v[212:213] op_sel_hi:[0,1,1]
	v_pk_fma_f32 v[184:185], v[82:83], v[188:189], v[142:143] op_sel:[1,1,0] op_sel_hi:[1,0,1] neg_lo:[1,0,0]
	v_pk_fma_f32 v[214:215], v[82:83], v[188:189], v[184:185] op_sel_hi:[0,1,1]
	v_pk_fma_f32 v[216:217], v[208:209], v[188:189], v[210:211] op_sel:[1,1,0] op_sel_hi:[1,0,1] neg_lo:[1,0,0]
	v_pk_fma_f32 v[186:187], v[208:209], v[188:189], v[216:217] op_sel_hi:[0,1,1]
	v_cvt_pk_bf16_f32 v190, v214, v215
	ds_write_b32 v191, v190 offset:11984
	v_cvt_pk_bf16_f32 v190, v186, v187
	ds_write_b32 v191, v190 offset:11712
	v_pk_fma_f32 v[212:213], v[82:83], v[146:147], v[148:149] op_sel:[1,1,0] op_sel_hi:[1,0,1] neg_lo:[1,0,0]
	v_pk_fma_f32 v[210:211], v[82:83], v[146:147], v[212:213] op_sel_hi:[0,1,1]
	v_pk_fma_f32 v[184:185], v[82:83], v[186:187], v[146:147] op_sel:[1,1,0] op_sel_hi:[1,0,1] neg_lo:[1,0,0]
	v_pk_fma_f32 v[214:215], v[82:83], v[186:187], v[184:185] op_sel_hi:[0,1,1]
	v_pk_fma_f32 v[216:217], v[208:209], v[186:187], v[210:211] op_sel:[1,1,0] op_sel_hi:[1,0,1] neg_lo:[1,0,0]
	v_pk_fma_f32 v[188:189], v[208:209], v[186:187], v[216:217] op_sel_hi:[0,1,1]
	v_cvt_pk_bf16_f32 v190, v214, v215
	ds_write_b32 v191, v190 offset:11440
	v_cvt_pk_bf16_f32 v190, v188, v189
	ds_write_b32 v191, v190 offset:11168
	v_pk_fma_f32 v[212:213], v[82:83], v[150:151], v[152:153] op_sel:[1,1,0] op_sel_hi:[1,0,1] neg_lo:[1,0,0]
	v_pk_fma_f32 v[210:211], v[82:83], v[150:151], v[212:213] op_sel_hi:[0,1,1]
	v_pk_fma_f32 v[184:185], v[82:83], v[188:189], v[150:151] op_sel:[1,1,0] op_sel_hi:[1,0,1] neg_lo:[1,0,0]
	v_pk_fma_f32 v[214:215], v[82:83], v[188:189], v[184:185] op_sel_hi:[0,1,1]
	v_pk_fma_f32 v[216:217], v[208:209], v[188:189], v[210:211] op_sel:[1,1,0] op_sel_hi:[1,0,1] neg_lo:[1,0,0]
	v_pk_fma_f32 v[186:187], v[208:209], v[188:189], v[216:217] op_sel_hi:[0,1,1]
	v_cvt_pk_bf16_f32 v190, v214, v215
	ds_write_b32 v191, v190 offset:10896
	v_cvt_pk_bf16_f32 v190, v186, v187
	ds_write_b32 v191, v190 offset:10624
	v_pk_fma_f32 v[212:213], v[82:83], v[154:155], v[156:157] op_sel:[1,1,0] op_sel_hi:[1,0,1] neg_lo:[1,0,0]
	v_pk_fma_f32 v[210:211], v[82:83], v[154:155], v[212:213] op_sel_hi:[0,1,1]
	v_pk_fma_f32 v[184:185], v[82:83], v[186:187], v[154:155] op_sel:[1,1,0] op_sel_hi:[1,0,1] neg_lo:[1,0,0]
	v_pk_fma_f32 v[214:215], v[82:83], v[186:187], v[184:185] op_sel_hi:[0,1,1]
	v_pk_fma_f32 v[216:217], v[208:209], v[186:187], v[210:211] op_sel:[1,1,0] op_sel_hi:[1,0,1] neg_lo:[1,0,0]
	v_pk_fma_f32 v[188:189], v[208:209], v[186:187], v[216:217] op_sel_hi:[0,1,1]
	v_cvt_pk_bf16_f32 v190, v214, v215
	ds_write_b32 v191, v190 offset:10352
	v_cvt_pk_bf16_f32 v190, v188, v189
	ds_write_b32 v191, v190 offset:10080
	v_pk_fma_f32 v[212:213], v[82:83], v[158:159], v[160:161] op_sel:[1,1,0] op_sel_hi:[1,0,1] neg_lo:[1,0,0]
	v_pk_fma_f32 v[210:211], v[82:83], v[158:159], v[212:213] op_sel_hi:[0,1,1]
	v_pk_fma_f32 v[184:185], v[82:83], v[188:189], v[158:159] op_sel:[1,1,0] op_sel_hi:[1,0,1] neg_lo:[1,0,0]
	v_pk_fma_f32 v[214:215], v[82:83], v[188:189], v[184:185] op_sel_hi:[0,1,1]
	v_pk_fma_f32 v[216:217], v[208:209], v[188:189], v[210:211] op_sel:[1,1,0] op_sel_hi:[1,0,1] neg_lo:[1,0,0]
	v_pk_fma_f32 v[186:187], v[208:209], v[188:189], v[216:217] op_sel_hi:[0,1,1]
	v_cvt_pk_bf16_f32 v190, v214, v215
	ds_write_b32 v191, v190 offset:9808
	v_cvt_pk_bf16_f32 v190, v186, v187
	ds_write_b32 v191, v190 offset:9536
	v_pk_fma_f32 v[212:213], v[82:83], v[162:163], v[164:165] op_sel:[1,1,0] op_sel_hi:[1,0,1] neg_lo:[1,0,0]
	v_pk_fma_f32 v[210:211], v[82:83], v[162:163], v[212:213] op_sel_hi:[0,1,1]
	v_pk_fma_f32 v[184:185], v[82:83], v[186:187], v[162:163] op_sel:[1,1,0] op_sel_hi:[1,0,1] neg_lo:[1,0,0]
	v_pk_fma_f32 v[214:215], v[82:83], v[186:187], v[184:185] op_sel_hi:[0,1,1]
	v_pk_fma_f32 v[216:217], v[208:209], v[186:187], v[210:211] op_sel:[1,1,0] op_sel_hi:[1,0,1] neg_lo:[1,0,0]
	v_pk_fma_f32 v[188:189], v[208:209], v[186:187], v[216:217] op_sel_hi:[0,1,1]
	v_cvt_pk_bf16_f32 v190, v214, v215
	ds_write_b32 v191, v190 offset:9264
	v_cvt_pk_bf16_f32 v190, v188, v189
	ds_write_b32 v191, v190 offset:8992
	v_pk_fma_f32 v[212:213], v[82:83], v[166:167], v[168:169] op_sel:[1,1,0] op_sel_hi:[1,0,1] neg_lo:[1,0,0]
	v_pk_fma_f32 v[210:211], v[82:83], v[166:167], v[212:213] op_sel_hi:[0,1,1]
	v_pk_fma_f32 v[184:185], v[82:83], v[188:189], v[166:167] op_sel:[1,1,0] op_sel_hi:[1,0,1] neg_lo:[1,0,0]
	v_pk_fma_f32 v[214:215], v[82:83], v[188:189], v[184:185] op_sel_hi:[0,1,1]
	v_pk_fma_f32 v[216:217], v[208:209], v[188:189], v[210:211] op_sel:[1,1,0] op_sel_hi:[1,0,1] neg_lo:[1,0,0]
	v_pk_fma_f32 v[186:187], v[208:209], v[188:189], v[216:217] op_sel_hi:[0,1,1]
	v_cvt_pk_bf16_f32 v190, v214, v215
	ds_write_b32 v191, v190 offset:8720
	v_mov_b32_e32 v36, v186
	v_mov_b32_e32 v37, v187
	v_cvt_pk_bf16_f32 v190, v186, v187
	ds_write_b32 v191, v190 offset:8448
	s_waitcnt vmcnt(0) lgkmcnt(0)
	ds_read_b128 v[36:39], v81 offset:8448
	s_waitcnt lgkmcnt(0)
	v_mfma_f32_16x16x32_bf16 v[32:35], v[36:39], v[32:35], 0
	ds_read_b128 v[36:39], v81 offset:8512
	s_waitcnt lgkmcnt(0)
	v_mfma_f32_16x16x32_bf16 v[28:31], v[36:39], v[28:31], v[32:35]
	s_nop 4
	ds_read_b128 v[32:35], v81 offset:8576
	s_waitcnt lgkmcnt(0)
	v_mfma_f32_16x16x32_bf16 v[24:27], v[32:35], v[24:27], v[28:31]
	s_nop 2
	ds_read_b128 v[28:31], v81 offset:8640
	s_waitcnt lgkmcnt(0)
	v_mfma_f32_16x16x32_bf16 v[20:23], v[28:31], v[20:23], v[24:27]
	s_nop 7
	v_pk_add_f32 v[24:25], v[0:1], v[20:21]
	v_and_or_b32 v0, v90, 15, v80
	v_add_u32_e32 v20, s6, v0
	v_ashrrev_i32_e32 v21, 31, v20
	v_lshrrev_b32_e32 v1, 2, v90
	v_lshl_add_u64 v[20:21], v[20:21], 2, s[76:77]
	v_and_b32_e32 v1, 12, v1
	global_load_dword v28, v[20:21], off
	v_add_u32_e32 v20, s8, v1
	v_ashrrev_i32_e32 v21, 31, v20
	v_ashrrev_i32_e32 v1, 31, v0
	v_lshlrev_b64 v[26:27], 9, v[20:21]
	v_lshl_add_u64 v[26:27], v[26:27], 0, v[0:1]
	v_lshl_add_u64 v[30:31], v[26:27], 1, s[36:37]
	global_load_ushort v29, v[30:31], off
	global_load_ushort v141, v[30:31], off offset:1024
	global_load_ushort v142, v[30:31], off offset:2048
	global_load_ushort v143, v[30:31], off offset:3072
	s_mov_b64 s[0:1], 0x4000
	v_lshl_add_u64 v[156:157], v[30:31], 0, s[0:1]
	global_load_ushort v144, v[156:157], off
	global_load_ushort v145, v[156:157], off offset:1024
	global_load_ushort v146, v[156:157], off offset:2048
	global_load_ushort v147, v[156:157], off offset:3072
	s_mov_b64 s[0:1], 0x8000
	v_lshl_add_u64 v[158:159], v[30:31], 0, s[0:1]
	global_load_ushort v148, v[158:159], off
	global_load_ushort v149, v[158:159], off offset:1024
	global_load_ushort v150, v[158:159], off offset:2048
	global_load_ushort v151, v[158:159], off offset:3072
	s_mov_b64 s[0:1], 0xc000
	v_lshl_add_u64 v[160:161], v[30:31], 0, s[0:1]
	global_load_ushort v152, v[160:161], off
	global_load_ushort v153, v[160:161], off offset:1024
	global_load_ushort v154, v[160:161], off offset:2048
	global_load_ushort v155, v[160:161], off offset:3072
	s_waitcnt vmcnt(0) lgkmcnt(0)
	v_lshlrev_b32_e32 v29, 16, v29
	v_fma_f32 v24, v28, v29, v24
	v_mul_f32_e32 v29, 0x3d372713, v24
	v_mul_f32_e32 v29, v24, v29
	v_fma_f32 v29, v24, v29, v24
	v_mul_f32_e32 v29, 0x3f4c422a, v29
	v_cmp_nlt_f32_e64 s[0:1], |v29|, s10
	s_and_saveexec_b64 s[2:3], s[0:1]
	s_xor_b64 s[0:1], exec, s[2:3]
	s_cbranch_execz .LBB0_1813
	v_add_f32_e64 v30, |v29|, |v29|
	v_mul_f32_e32 v31, 0x3fb8aa3b, v30
	v_rndne_f32_e32 v32, v31
	s_mov_b32 s2, 0x3fb8aa3b
	v_sub_f32_e32 v33, v31, v32
	v_fma_f32 v31, v30, s2, -v31
	v_fmac_f32_e32 v31, 0x32a5705f, v30
	v_add_f32_e32 v31, v33, v31
	v_cvt_i32_f32_e32 v32, v32
	v_exp_f32_e32 v31, v31
	s_mov_b32 s2, 0xc2ce8ed0
	v_cmp_ngt_f32_e32 vcc, s2, v30
	s_mov_b32 s2, 0x42b17218
	v_ldexp_f32 v31, v31, v32
	v_cndmask_b32_e32 v31, 0, v31, vcc
	v_cmp_nlt_f32_e32 vcc, s2, v30
	s_nop 1
	v_cndmask_b32_e32 v30, v235, v31, vcc
	v_add_f32_e32 v30, 1.0, v30
	v_rcp_f32_e32 v30, v30
	s_nop 0
	v_fma_f32 v30, v30, -2.0, 1.0
